# v6 plus S5 pass-2: next-iteration silu(z_b) operands land in loop-free registers and are unpacked at first use instead of after vmcnt(0) at the loop top
# speedup vs baseline: 1.0201x; 1.0022x over previous
; #define LAS __attribute__((address_space(3)))
; __device__ __forceinline__ bf16x8 pack8(f32x4 lo, f32x4 hi) { v4u w; w.x = pk2(lo[0], lo[1]); w.y = pk2(lo[2], lo[3]); w.z = pk2(hi[0], hi[1]); w.w = pk2(hi[2], hi[3]); return __builtin_bit_cast(bf16x8, w); }
; __device__ __forceinline__ void gmlp_compute(GmlpRegs& R, const Args& a, const Ctx& C, int c, int hd) {
;     ...
;     const float lg = R.lg, lb = R.lb;
;     bf16x8 af[4];
; #pragma unroll
;     for (int ks = 0; ks < 4; ++ks) { f32x4 lo, hi;
; #pragma unroll
;         for (int e = 0; e < 8; ++e) { const int sl = 32 * ks + 8 * q + e;
;             const float v = __uint_as_float((unsigned)*(const LAS unsigned short*)(VL + sl * 260 + (16 * w + fr) * 2) << 16);
;             const float x = (v - ST[2 * sl]) * ST[2 * sl + 1] * lg + lb; if (e < 4) lo[e] = x; else hi[e - 4] = x; }
;         af[ks] = pack8(lo, hi); }
.LBB0_973:
	s_or_b64 exec, exec, s[4:5]
	s_waitcnt lgkmcnt(0)
	s_barrier
	v_add_u32_e32 v18, v165, v184
	ds_read_b128 v[2:5], v183
	ds_read_u16 v6, v18 offset:34816
	ds_read_u16 v7, v18 offset:35076
	ds_read_u16 v14, v18 offset:35596
	ds_read_u16 v15, v18 offset:36116
	ds_read_u16 v19, v18 offset:36636
	ds_read_u16 v20, v18 offset:43396
	ds_read_u16 v21, v18 offset:43916
	ds_read_u16 v22, v18 offset:44436
	s_waitcnt lgkmcnt(6)
	v_lshlrev_b32_e32 v11, 16, v7
	v_lshlrev_b32_e32 v10, 16, v6
	ds_read_b128 v[6:9], v168
	v_mov_b32_e32 v12, v2
	v_mov_b32_e32 v13, v4
	v_pk_add_f32 v[10:11], v[10:11], v[12:13] neg_lo:[0,1] neg_hi:[0,1]
	v_mov_b32_e32 v4, v3
	v_pk_mul_f32 v[2:3], v[4:5], v[10:11]
	s_waitcnt lgkmcnt(0)
	v_mov_b32_e32 v5, v8
	v_pk_fma_f32 v[10:11], v[98:99], v[2:3], v[100:101]
	v_add_u32_e32 v2, v165, v167
	v_lshlrev_b32_e32 v3, 16, v14
	ds_read_u16 v4, v2 offset:34816
	ds_read_u16 v14, v2 offset:35336
	ds_read_u16 v23, v2 offset:35856
	ds_read_u16 v24, v2 offset:42616
	ds_read_u16 v25, v2 offset:43136
	ds_read_u16 v113, v18 offset:61596
	s_waitcnt lgkmcnt(5)
	v_lshlrev_b32_e32 v2, 16, v4
	v_mov_b32_e32 v4, v6
	v_pk_add_f32 v[2:3], v[2:3], v[4:5] neg_lo:[0,1] neg_hi:[0,1]
	v_mov_b32_e32 v8, v7
	v_pk_mul_f32 v[6:7], v[8:9], v[2:3]
	ds_read_b128 v[2:5], v163
	v_pk_fma_f32 v[12:13], v[98:99], v[6:7], v[100:101]
	ds_read_b128 v[6:9], v166
	v_lshlrev_b32_e32 v15, 16, v15
	s_waitcnt lgkmcnt(6)
	v_lshlrev_b32_e32 v14, 16, v14
	s_waitcnt lgkmcnt(1)
	v_mov_b32_e32 v16, v2
	v_mov_b32_e32 v17, v4
	v_pk_add_f32 v[14:15], v[14:15], v[16:17] neg_lo:[0,1] neg_hi:[0,1]
	v_mov_b32_e32 v4, v3
	v_pk_mul_f32 v[2:3], v[4:5], v[14:15]
	s_waitcnt lgkmcnt(0)
	v_mov_b32_e32 v14, v6
	v_pk_fma_f32 v[4:5], v[98:99], v[2:3], v[100:101]
	v_lshlrev_b32_e32 v3, 16, v19
	v_lshlrev_b32_e32 v2, 16, v23
	v_mov_b32_e32 v15, v8
	v_pk_add_f32 v[2:3], v[2:3], v[14:15] neg_lo:[0,1] neg_hi:[0,1]
	v_mov_b32_e32 v8, v7
	v_pk_mul_f32 v[2:3], v[8:9], v[2:3]
	ds_read_b128 v[6:9], v185
	v_pk_fma_f32 v[14:15], v[98:99], v[2:3], v[100:101]
	v_cvt_pk_bf16_f32 v2, v10, v11
	v_cvt_pk_bf16_f32 v3, v12, v13
	ds_read_b128 v[10:13], v186
	v_cvt_pk_bf16_f32 v4, v4, v5
	v_cvt_pk_bf16_f32 v5, v14, v15
	v_lshlrev_b32_e32 v15, 16, v20
	v_lshlrev_b32_e32 v14, 16, v24
	s_waitcnt lgkmcnt(1)
	v_mov_b32_e32 v16, v6
	v_mov_b32_e32 v17, v8
	v_pk_add_f32 v[14:15], v[14:15], v[16:17] neg_lo:[0,1] neg_hi:[0,1]
	v_mov_b32_e32 v8, v7
	v_pk_mul_f32 v[6:7], v[8:9], v[14:15]
	s_waitcnt lgkmcnt(0)
	v_mov_b32_e32 v8, v10
	v_pk_fma_f32 v[14:15], v[98:99], v[6:7], v[100:101]
	v_lshlrev_b32_e32 v7, 16, v21
	v_lshlrev_b32_e32 v6, 16, v25
	v_mov_b32_e32 v9, v12
	v_pk_add_f32 v[16:17], v[6:7], v[8:9] neg_lo:[0,1] neg_hi:[0,1]
	ds_read_u16 v19, v187 offset:34816
	ds_read_u16 v20, v187 offset:35336
	ds_read_u16 v21, v187 offset:42096
	ds_read_b128 v[6:9], v188
	v_mov_b32_e32 v12, v11
	v_pk_mul_f32 v[10:11], v[12:13], v[16:17]
	v_lshlrev_b32_e32 v13, 16, v22
	s_waitcnt lgkmcnt(3)
	v_lshlrev_b32_e32 v12, 16, v19
	s_waitcnt lgkmcnt(0)
	v_mov_b32_e32 v16, v6
	v_mov_b32_e32 v17, v8
	v_pk_add_f32 v[12:13], v[12:13], v[16:17] neg_lo:[0,1] neg_hi:[0,1]
	v_mov_b32_e32 v8, v7
	v_pk_mul_f32 v[6:7], v[8:9], v[12:13]
	v_pk_fma_f32 v[10:11], v[98:99], v[10:11], v[100:101]
	v_pk_fma_f32 v[12:13], v[98:99], v[6:7], v[100:101]
	ds_read_b128 v[6:9], v189
	ds_read_u16 v16, v18 offset:44956
	ds_read_u16 v22, v18 offset:51716
	ds_read_u16 v23, v18 offset:52236
	ds_read_u16 v24, v18 offset:52756
	ds_read_u16 v26, v18 offset:53276
	ds_read_u16 v27, v18 offset:60036
	ds_read_u16 v28, v18 offset:60556
	ds_read_u16 v36, v18 offset:61076
	s_waitcnt lgkmcnt(7)
	v_lshlrev_b32_e32 v17, 16, v16
	v_lshlrev_b32_e32 v16, 16, v20
	v_mov_b32_e32 v18, v6
	v_mov_b32_e32 v19, v8
	v_pk_add_f32 v[16:17], v[16:17], v[18:19] neg_lo:[0,1] neg_hi:[0,1]
	v_mov_b32_e32 v8, v7
	v_pk_mul_f32 v[6:7], v[8:9], v[16:17]
	ds_read_u16 v25, v187 offset:42616
	ds_read_u16 v29, v187 offset:43136
	v_pk_fma_f32 v[16:17], v[98:99], v[6:7], v[100:101]
	v_cvt_pk_bf16_f32 v7, v10, v11
	v_cvt_pk_bf16_f32 v8, v12, v13
	ds_read_b128 v[10:13], v190
	v_cvt_pk_bf16_f32 v6, v14, v15
	v_cvt_pk_bf16_f32 v9, v16, v17
	ds_read_b128 v[14:17], v191
	s_waitcnt lgkmcnt(10)
	v_lshlrev_b32_e32 v19, 16, v22
	v_lshlrev_b32_e32 v18, 16, v21
	s_waitcnt lgkmcnt(1)
	v_mov_b32_e32 v20, v10
	v_mov_b32_e32 v21, v12
	v_pk_add_f32 v[18:19], v[18:19], v[20:21] neg_lo:[0,1] neg_hi:[0,1]
	v_mov_b32_e32 v12, v11
	v_pk_mul_f32 v[10:11], v[12:13], v[18:19]
	s_waitcnt lgkmcnt(0)
	v_mov_b32_e32 v12, v14
	v_pk_fma_f32 v[18:19], v[98:99], v[10:11], v[100:101]
	v_lshlrev_b32_e32 v11, 16, v23
	v_lshlrev_b32_e32 v10, 16, v25
	v_mov_b32_e32 v13, v16
	v_pk_add_f32 v[10:11], v[10:11], v[12:13] neg_lo:[0,1] neg_hi:[0,1]
	v_mov_b32_e32 v16, v15
	v_pk_mul_f32 v[14:15], v[16:17], v[10:11]
	ds_read_b128 v[10:13], v192
	v_pk_fma_f32 v[20:21], v[98:99], v[14:15], v[100:101]
	ds_read_b128 v[14:17], v194
	v_lshlrev_b32_e32 v23, 16, v24
	v_lshlrev_b32_e32 v22, 16, v29
	s_waitcnt lgkmcnt(1)
	v_mov_b32_e32 v24, v10
	v_mov_b32_e32 v25, v12
	v_pk_add_f32 v[22:23], v[22:23], v[24:25] neg_lo:[0,1] neg_hi:[0,1]
	v_mov_b32_e32 v12, v11
	v_pk_mul_f32 v[10:11], v[12:13], v[22:23]
	s_waitcnt lgkmcnt(0)
	v_mov_b32_e32 v22, v14
	v_pk_fma_f32 v[12:13], v[98:99], v[10:11], v[100:101]
	ds_read_u16 v10, v193 offset:34816
	ds_read_u16 v24, v193 offset:41576
	ds_read_u16 v29, v193 offset:42096
	ds_read_u16 v38, v193 offset:42616
	ds_read_u16 v121, v193 offset:43136
	v_lshlrev_b32_e32 v11, 16, v26
	s_waitcnt lgkmcnt(4)
; #define LAS __attribute__((address_space(3)))
; #define MFMA16(A, B, Cc) __builtin_amdgcn_mfma_f32_16x16x32_bf16((A), (B), (Cc), 0, 0, 0)
; #define PIN(x) asm volatile("" : "+v"(x))
; __device__ __forceinline__ float bf_lo(unsigned w) { return __uint_as_float(w << 16); }
; __device__ __forceinline__ unsigned pk4f8(float a, float b, float c, float d) { int p = __builtin_amdgcn_cvt_pk_fp8_f32(sat8(a), sat8(b), 0, false); p = __builtin_amdgcn_cvt_pk_fp8_f32(sat8(c), sat8(d), p, true); return (unsigned)p; }
; __device__ __forceinline__ float bf_hi(unsigned w) { return __uint_as_float(w & 0xffff0000u); }
; __device__ __forceinline__ bf16x8 pack8(f32x4 lo, f32x4 hi) { v4u w; w.x = pk2(lo[0], lo[1]); w.y = pk2(lo[2], lo[3]); w.z = pk2(hi[0], hi[1]); w.w = pk2(hi[2], hi[3]); return __builtin_bit_cast(bf16x8, w); }
; __device__ __forceinline__ void gmlp_compute(GmlpRegs& R, const Args& a, const Ctx& C, int c, int hd) {
;     ...
; #pragma unroll
;     for (int ks = 0; ks < 4; ++ks) { f32x4 lo, hi;
; #pragma unroll
;         for (int e = 0; e < 8; ++e) { const int sl = 32 * ks + 8 * q + e;
;             const float v = __uint_as_float((unsigned)*(const LAS unsigned short*)(VL + sl * 260 + (16 * w + fr) * 2) << 16);
;             const float x = (v - ST[2 * sl]) * ST[2 * sl + 1] * lg + lb; if (e < 4) lo[e] = x; else hi[e - 4] = x; }
;         af[ks] = pack8(lo, hi); }
;     f32x4 acc[8];
; #pragma unroll
;     for (int nt = 0; nt < 8; ++nt) { acc[nt] = (f32x4){0.f, 0.f, 0.f, 0.f};
; #pragma unroll
;         for (int ks = 0; ks <= nt / 2; ++ks) acc[nt] = MFMA16(af[ks], *(const LAS bf16x8*)(WL + (16 * nt + fr) * 272 + (32 * ks + 8 * q) * 2), acc[nt]); }
; #pragma unroll
;     for (int nt = 0; nt < 8; ++nt) PIN(R.uq[nt]);
; #pragma unroll
;     for (int nt = 0; nt < 8; ++nt) { const size_t row = T0 + 16 * nt + fr; const float bs = R.bsv[nt];
;         const float o0 = bf_lo(R.uq[nt].x) * (acc[nt][0] + bs), o1 = bf_hi(R.uq[nt].x) * (acc[nt][1] + bs);
;         const float o2 = bf_lo(R.uq[nt].y) * (acc[nt][2] + bs), o3 = bf_hi(R.uq[nt].y) * (acc[nt][3] + bs);
;         *(unsigned*)((unsigned char*)Y + row * DM + chs) = pk4f8(o0, o1, o2, o3); }
	v_lshlrev_b32_e32 v10, 16, v10
	v_mov_b32_e32 v23, v16
	v_pk_add_f32 v[10:11], v[10:11], v[22:23] neg_lo:[0,1] neg_hi:[0,1]
	v_mov_b32_e32 v16, v15
	v_pk_mul_f32 v[10:11], v[16:17], v[10:11]
	ds_read_b128 v[14:17], v195
	v_pk_fma_f32 v[22:23], v[98:99], v[10:11], v[100:101]
	v_cvt_pk_bf16_f32 v10, v18, v19
	v_cvt_pk_bf16_f32 v11, v20, v21
	v_cvt_pk_bf16_f32 v12, v12, v13
	v_cvt_pk_bf16_f32 v13, v22, v23
	v_lshlrev_b32_e32 v23, 16, v27
	s_waitcnt lgkmcnt(4)
	v_lshlrev_b32_e32 v22, 16, v24
	ds_read_b128 v[18:21], v196
	s_waitcnt lgkmcnt(1)
	v_mov_b32_e32 v24, v14
	v_mov_b32_e32 v25, v16
	v_pk_add_f32 v[26:27], v[22:23], v[24:25] neg_lo:[0,1] neg_hi:[0,1]
	v_mov_b32_e32 v16, v15
	v_add_u32_e32 v126, v199, v200
	v_pk_mul_f32 v[14:15], v[16:17], v[26:27]
	v_lshlrev_b32_e32 v31, 16, v28
	v_lshlrev_b32_e32 v30, 16, v29
	ds_read_b128 v[26:29], v126 offset:8704
	s_waitcnt lgkmcnt(1)
	v_mov_b32_e32 v32, v18
	v_mov_b32_e32 v33, v20
	v_pk_add_f32 v[34:35], v[30:31], v[32:33] neg_lo:[0,1] neg_hi:[0,1]
	ds_read_b128 v[30:33], v126 offset:8768
	v_mov_b32_e32 v20, v19
	s_waitcnt lgkmcnt(1)
	v_mfma_f32_16x16x32_bf16 v[26:29], v[2:5], v[26:29], 0
	v_mul_f32_e64 v34, v20, v34
	v_mul_f32_e64 v35, v21, v35
	ds_read_b128 v[18:21], v126 offset:13056
	v_lshlrev_b32_e32 v46, 16, v38
	ds_read_b128 v[38:41], v126 offset:17408
	ds_read_b128 v[42:45], v126 offset:17472
	s_waitcnt lgkmcnt(3)
	v_mfma_f32_16x16x32_bf16 v[26:29], v[6:9], v[30:33], v[26:29]
	v_fma_f32 v92, v98, v34, v100
	v_fma_f32 v93, v99, v35, v101
	v_lshlrev_b32_e32 v47, 16, v36
	ds_read_b128 v[30:33], v126 offset:13120
	ds_read_b128 v[34:37], v197
	s_waitcnt lgkmcnt(4)
	v_mfma_f32_16x16x32_bf16 v[18:21], v[2:5], v[18:21], 0
	v_fma_f32 v88, v98, v14, v100
	v_fma_f32 v89, v99, v15, v101
	ds_read_b128 v[22:25], v126
	ds_read_b128 v[14:17], v126 offset:4352
	s_waitcnt lgkmcnt(5)
	v_mfma_f32_16x16x32_bf16 v[38:41], v[2:5], v[38:41], 0
	s_lshl_b64 s[4:5], s[70:71], 11
	s_mov_b64 s[8:9], 0x2300000
	v_readlane_b32 s16, v249, 1
	s_waitcnt lgkmcnt(3)
	v_mfma_f32_16x16x32_bf16 v[18:21], v[6:9], v[30:33], v[18:21]
	ds_read_b128 v[30:33], v198
	s_waitcnt lgkmcnt(3)
	v_mov_b32_e32 v48, v34
	v_mov_b32_e32 v49, v36
	v_pk_add_f32 v[90:91], v[46:47], v[48:49] neg_lo:[0,1] neg_hi:[0,1]
	v_mov_b32_e32 v36, v35
	ds_read_b128 v[46:49], v126 offset:17536
	v_mfma_f32_16x16x32_bf16 v[38:41], v[6:9], v[42:45], v[38:41]
	v_mul_f32_e64 v42, v36, v90
	v_mul_f32_e64 v43, v37, v91
	ds_read_b128 v[34:37], v126 offset:21760
	v_pk_fma_f32 v[122:123], v[98:99], v[42:43], v[100:101]
	ds_read_b128 v[42:45], v126 offset:21824
	s_waitcnt lgkmcnt(1)
	v_mfma_f32_16x16x32_bf16 v[34:37], v[2:5], v[34:37], 0
	v_lshlrev_b32_e32 v91, 16, v113
	v_lshlrev_b32_e32 v90, 16, v121
	v_mov_b32_e32 v124, v30
	v_mfma_f32_16x16x32_bf16 v[38:41], v[10:13], v[46:49], v[38:41]
	ds_read_b128 v[46:49], v126 offset:21888
	v_mov_b32_e32 v125, v32
	v_pk_add_f32 v[90:91], v[90:91], v[124:125] neg_lo:[0,1] neg_hi:[0,1]
	s_waitcnt lgkmcnt(1)
	v_mfma_f32_16x16x32_bf16 v[34:37], v[6:9], v[42:45], v[34:37]
	ds_read_b128 v[42:45], v126 offset:26112
	v_mov_b32_e32 v32, v31
	v_readlane_b32 s17, v249, 2
	s_waitcnt lgkmcnt(1)
	v_mfma_f32_16x16x32_bf16 v[34:37], v[10:13], v[46:49], v[34:37]
	v_mul_f32_e64 v46, v32, v90
	v_mul_f32_e64 v47, v33, v91
	ds_read_b128 v[30:33], v126 offset:26176
	v_pk_fma_f32 v[98:99], v[98:99], v[46:47], v[100:101]
	s_waitcnt lgkmcnt(1)
	v_mfma_f32_16x16x32_bf16 v[42:45], v[2:5], v[42:45], 0
	v_cvt_pk_bf16_f32 v46, v88, v89
	ds_read_b128 v[88:91], v126 offset:26240
	v_cvt_pk_bf16_f32 v47, v92, v93
	s_waitcnt lgkmcnt(1)
	v_mfma_f32_16x16x32_bf16 v[30:33], v[6:9], v[30:33], v[42:45]
	v_cvt_pk_bf16_f32 v48, v122, v123
	v_cvt_pk_bf16_f32 v49, v98, v99
	v_readlane_b32 s18, v249, 3
	ds_read_b128 v[42:45], v126 offset:26304
	s_waitcnt lgkmcnt(1)
	v_mfma_f32_16x16x32_bf16 v[30:33], v[10:13], v[88:91], v[30:33]
	v_readlane_b32 s19, v249, 4
	v_readlane_b32 s20, v249, 5
	v_readlane_b32 s21, v249, 6
	s_waitcnt lgkmcnt(0)
	v_mfma_f32_16x16x32_bf16 v[30:33], v[46:49], v[42:45], v[30:33]
	ds_read_b128 v[42:45], v126 offset:30464
	ds_read_b128 v[88:91], v126 offset:30528
	v_readlane_b32 s22, v249, 7
	v_readlane_b32 s23, v249, 8
	v_mfma_f32_16x16x32_bf16 v[22:25], v[2:5], v[22:25], 0
	v_readlane_b32 s24, v249, 9
	v_readlane_b32 s25, v249, 10
	v_readlane_b32 s26, v249, 11
	v_mfma_f32_16x16x32_bf16 v[14:17], v[2:5], v[14:17], 0
	v_readlane_b32 s27, v249, 12
	v_readlane_b32 s28, v249, 13
	v_readlane_b32 s29, v249, 14
	s_waitcnt lgkmcnt(1)
	v_mfma_f32_16x16x32_bf16 v[2:5], v[2:5], v[42:45], 0
	v_readlane_b32 s30, v249, 15
	v_readlane_b32 s31, v249, 16
	s_mov_b64 s[14:15], s[22:23]
	s_waitcnt lgkmcnt(0)
	v_mfma_f32_16x16x32_bf16 v[2:5], v[6:9], v[88:91], v[2:5]
	ds_read_b128 v[6:9], v126 offset:30592
	ds_read_b128 v[42:45], v126 offset:30656
	s_waitcnt vmcnt(23)
	s_waitcnt vmcnt(22)
	s_waitcnt lgkmcnt(1)
	v_mfma_f32_16x16x32_bf16 v[2:5], v[10:13], v[6:9], v[2:5]
	v_lshlrev_b32_e32 v6, 16, v110
	v_add_f32_e32 v7, v161, v22
	v_mul_f32_e32 v6, v7, v6
	v_and_b32_e32 v7, 0xffff0000, v110
	v_add_f32_e32 v8, v161, v23
	v_mul_f32_e32 v7, v8, v7
	v_med3_f32 v6, v6, s1, v128
	v_med3_f32 v7, v7, s1, v128
	v_mov_b32_e32 v11, 0
	v_lshlrev_b32_e32 v8, 16, v111
	v_add_f32_e32 v9, v161, v24
	v_cvt_pk_fp8_f32 v11, v6, v7
	v_mul_f32_e32 v8, v9, v8
	v_and_b32_e32 v9, 0xffff0000, v111
	v_add_f32_e32 v10, v161, v25
	v_mul_f32_e32 v6, v10, v9
	v_med3_f32 v7, v8, s1, v128
	v_med3_f32 v6, v6, s1, v128
	v_cvt_pk_fp8_f32 v11, v7, v6 op_sel:[0,0,1]
	v_lshlrev_b32_e32 v8, 16, v118
	v_add_f32_e32 v9, v160, v14
	v_mul_f32_e32 v8, v9, v8
	v_and_b32_e32 v9, 0xffff0000, v118
	v_add_f32_e32 v10, v160, v15
	v_lshlrev_b64 v[6:7], 11, v[116:117]
	v_mul_f32_e32 v9, v10, v9
	v_lshl_add_u64 v[6:7], v[142:143], 0, v[6:7]
	v_med3_f32 v8, v8, s1, v128
	v_med3_f32 v9, v9, s1, v128
	v_mov_b32_e32 v13, 0
	s_waitcnt vmcnt(21)
; #define LAS __attribute__((address_space(3)))
; __device__ __forceinline__ float bf_lo(unsigned w) { return __uint_as_float(w << 16); }
; __device__ __forceinline__ unsigned pk4f8(float a, float b, float c, float d) { int p = __builtin_amdgcn_cvt_pk_fp8_f32(sat8(a), sat8(b), 0, false); p = __builtin_amdgcn_cvt_pk_fp8_f32(sat8(c), sat8(d), p, true); return (unsigned)p; }
; __device__ __forceinline__ float bf_hi(unsigned w) { return __uint_as_float(w & 0xffff0000u); }
; __device__ __forceinline__ void s5_prompt_task(const Args& a, const Ctx& C, int b, int g, v4u (&xv)[8]) {
;     const bf16* PROJ = (const bf16*)(a.ws + WS_PROJ); bf16* Y = (bf16*)(a.ws + WS_Y);
;     LAS unsigned char* XS = C.lds;
;     LAS float* SH = (LAS float*)(C.lds + 67584);
;     LAS float* TW = (LAS float*)(C.lds + 67584 + 128 * 132 * 4);
;     const int lane = C.lane, n = lane & 15, q = lane >> 4, w = C.wave;
;     const size_t row0 = (size_t)b * SEQ;
;     const bf16* XBg = (const bf16*)(a.ws + WS_XB) + ((size_t)g * MP + row0) * 16; const bf16* ZBg = (const bf16*)(a.ws + WS_ZB) + ((size_t)g * MP + row0) * 16;
; __device__ __forceinline__ void gmlp_compute(GmlpRegs& R, const Args& a, const Ctx& C, int c, int hd) {
;     ...
;     for (int nt = 0; nt < 8; ++nt) { const size_t row = T0 + 16 * nt + fr; const float bs = R.bsv[nt];
;         const float o0 = bf_lo(R.uq[nt].x) * (acc[nt][0] + bs), o1 = bf_hi(R.uq[nt].x) * (acc[nt][1] + bs);
;         const float o2 = bf_lo(R.uq[nt].y) * (acc[nt][2] + bs), o3 = bf_hi(R.uq[nt].y) * (acc[nt][3] + bs);
;         *(unsigned*)((unsigned char*)Y + row * DM + chs) = pk4f8(o0, o1, o2, o3); }
	s_waitcnt vmcnt(20)
	s_waitcnt vmcnt(19)
	s_waitcnt vmcnt(18)
	s_waitcnt vmcnt(17)
	s_waitcnt vmcnt(16)
	global_store_dword v[6:7], v11, off
	v_lshlrev_b32_e32 v10, 16, v119
	v_add_f32_e32 v11, v160, v16
	v_cvt_pk_fp8_f32 v13, v8, v9
	v_mul_f32_e32 v10, v11, v10
	v_and_b32_e32 v11, 0xffff0000, v119
	v_add_f32_e32 v12, v160, v17
	v_mul_f32_e32 v8, v12, v11
	v_med3_f32 v9, v10, s1, v128
	v_med3_f32 v8, v8, s1, v128
	v_cvt_pk_fp8_f32 v13, v9, v8 op_sel:[0,0,1]
	v_add_co_u32_e32 v8, vcc, s2, v6
	v_add_f32_e32 v10, v159, v27
	s_nop 0
	v_addc_co_u32_e32 v9, vcc, 0, v7, vcc
	global_store_dword v[8:9], v13, off
	v_lshlrev_b32_e32 v8, 16, v114
	v_add_f32_e32 v9, v159, v26
	v_mul_f32_e32 v8, v9, v8
	v_and_b32_e32 v9, 0xffff0000, v114
	v_mul_f32_e32 v9, v10, v9
	v_med3_f32 v8, v8, s1, v128
	v_med3_f32 v9, v9, s1, v128
	v_mov_b32_e32 v13, 0
	v_lshlrev_b32_e32 v10, 16, v115
	v_add_f32_e32 v11, v159, v28
	v_cvt_pk_fp8_f32 v13, v8, v9
	v_mul_f32_e32 v10, v11, v10
	v_and_b32_e32 v11, 0xffff0000, v115
	v_add_f32_e32 v12, v159, v29
	v_mul_f32_e32 v8, v12, v11
	v_med3_f32 v9, v10, s1, v128
	v_med3_f32 v8, v8, s1, v128
	v_cvt_pk_fp8_f32 v13, v9, v8 op_sel:[0,0,1]
	v_add_co_u32_e32 v8, vcc, s33, v6
	v_add_f32_e32 v10, v156, v19
	s_nop 0
	v_addc_co_u32_e32 v9, vcc, 0, v7, vcc
	global_store_dword v[8:9], v13, off
	v_lshlrev_b32_e32 v8, 16, v108
	v_add_f32_e32 v9, v156, v18
	v_mul_f32_e32 v8, v9, v8
	v_and_b32_e32 v9, 0xffff0000, v108
	v_mul_f32_e32 v9, v10, v9
	v_med3_f32 v8, v8, s1, v128
	v_med3_f32 v9, v9, s1, v128
	v_mov_b32_e32 v13, 0
	v_lshlrev_b32_e32 v10, 16, v109
	v_add_f32_e32 v11, v156, v20
	v_cvt_pk_fp8_f32 v13, v8, v9
	v_mul_f32_e32 v10, v11, v10
	v_and_b32_e32 v11, 0xffff0000, v109
	v_add_f32_e32 v12, v156, v21
	v_mul_f32_e32 v8, v12, v11
	v_med3_f32 v9, v10, s1, v128
	v_med3_f32 v8, v8, s1, v128
	v_cvt_pk_fp8_f32 v13, v9, v8 op_sel:[0,0,1]
	v_add_co_u32_e32 v8, vcc, s74, v6
	v_add_f32_e32 v10, v154, v39
	s_nop 0
	v_addc_co_u32_e32 v9, vcc, 0, v7, vcc
	global_store_dword v[8:9], v13, off
	v_lshlrev_b32_e32 v8, 16, v106
	v_add_f32_e32 v9, v154, v38
	v_mul_f32_e32 v8, v9, v8
	v_and_b32_e32 v9, 0xffff0000, v106
	v_mul_f32_e32 v9, v10, v9
	v_med3_f32 v8, v8, s1, v128
	v_med3_f32 v9, v9, s1, v128
	v_mov_b32_e32 v13, 0
	v_lshlrev_b32_e32 v10, 16, v107
	v_add_f32_e32 v11, v154, v40
	v_cvt_pk_fp8_f32 v13, v8, v9
	v_mul_f32_e32 v10, v11, v10
	v_and_b32_e32 v11, 0xffff0000, v107
	v_add_f32_e32 v12, v154, v41
	v_mul_f32_e32 v8, v12, v11
	v_med3_f32 v9, v10, s1, v128
	v_med3_f32 v8, v8, s1, v128
	v_cvt_pk_fp8_f32 v13, v9, v8 op_sel:[0,0,1]
	v_add_co_u32_e32 v8, vcc, s75, v6
	v_add_f32_e32 v10, v152, v35
	s_nop 0
	v_addc_co_u32_e32 v9, vcc, 0, v7, vcc
	global_store_dword v[8:9], v13, off
	v_lshlrev_b32_e32 v8, 16, v104
	v_add_f32_e32 v9, v152, v34
	v_mul_f32_e32 v8, v9, v8
	v_and_b32_e32 v9, 0xffff0000, v104
	v_mul_f32_e32 v9, v10, v9
	v_med3_f32 v8, v8, s1, v128
	v_med3_f32 v9, v9, s1, v128
	v_mov_b32_e32 v13, 0
	v_lshlrev_b32_e32 v10, 16, v105
	v_add_f32_e32 v11, v152, v36
	v_cvt_pk_fp8_f32 v13, v8, v9
	v_mul_f32_e32 v10, v11, v10
	v_and_b32_e32 v11, 0xffff0000, v105
	v_add_f32_e32 v12, v152, v37
	v_mul_f32_e32 v8, v12, v11
	v_med3_f32 v9, v10, s1, v128
	v_med3_f32 v8, v8, s1, v128
	v_cvt_pk_fp8_f32 v13, v9, v8 op_sel:[0,0,1]
	v_add_co_u32_e32 v8, vcc, s76, v6
	v_add_f32_e32 v10, v151, v31
	s_nop 0
	v_addc_co_u32_e32 v9, vcc, 0, v7, vcc
	global_store_dword v[8:9], v13, off
	v_lshlrev_b32_e32 v8, 16, v102
	v_add_f32_e32 v9, v151, v30
	v_mul_f32_e32 v8, v9, v8
	v_and_b32_e32 v9, 0xffff0000, v102
	v_mul_f32_e32 v9, v10, v9
	v_med3_f32 v8, v8, s1, v128
	v_med3_f32 v9, v9, s1, v128
	v_mov_b32_e32 v13, 0
	v_lshlrev_b32_e32 v10, 16, v103
	v_add_f32_e32 v11, v151, v32
	v_cvt_pk_fp8_f32 v13, v8, v9
	v_mul_f32_e32 v10, v11, v10
	v_and_b32_e32 v11, 0xffff0000, v103
	v_add_f32_e32 v12, v151, v33
	v_mul_f32_e32 v8, v12, v11
	v_med3_f32 v9, v10, s1, v128
	v_med3_f32 v8, v8, s1, v128
	s_waitcnt lgkmcnt(0)
	v_mfma_f32_16x16x32_bf16 v[2:5], v[46:49], v[42:45], v[2:5]
	v_cvt_pk_fp8_f32 v13, v9, v8 op_sel:[0,0,1]
	v_add_co_u32_e32 v8, vcc, s77, v6
	v_mov_b32_e32 v111, 0
	s_nop 0
	v_addc_co_u32_e32 v9, vcc, 0, v7, vcc
	global_store_dword v[8:9], v13, off
	v_lshlrev_b32_e32 v8, 16, v96
	s_nop 0
	v_add_f32_e32 v2, v150, v2
	v_mul_f32_e32 v2, v2, v8
	v_and_b32_e32 v8, 0xffff0000, v96
	v_add_f32_e32 v3, v150, v3
	v_mul_f32_e32 v3, v3, v8
	v_lshlrev_b32_e32 v8, 16, v97
	v_add_f32_e32 v4, v150, v4
	v_mul_f32_e32 v4, v4, v8
	v_and_b32_e32 v8, 0xffff0000, v97
	v_add_f32_e32 v5, v150, v5
	v_med3_f32 v2, v2, s1, v128
	v_med3_f32 v3, v3, s1, v128
	v_mov_b32_e32 v9, 0
	v_cvt_pk_fp8_f32 v9, v2, v3
	v_mul_f32_e32 v2, v5, v8
	v_med3_f32 v3, v4, s1, v128
	v_med3_f32 v2, v2, s1, v128
	s_mul_i32 s1, s0, 0x2100
	s_add_u32 s4, s1, s4
	s_addc_u32 s5, 0, s5
	s_lshl_b64 s[4:5], s[4:5], 5
	s_lshl_b32 s1, s0, 9
	s_lshl_b32 s2, s0, 12
	s_add_u32 s6, s94, s1
	v_cvt_pk_fp8_f32 v9, v3, v2 op_sel:[0,0,1]
	v_add_co_u32_e32 v2, vcc, s78, v6
	v_lshlrev_b32_e32 v110, 2, v153
	s_addc_u32 s7, s95, 0
	v_addc_co_u32_e32 v3, vcc, 0, v7, vcc
	v_lshl_add_u64 v[18:19], s[6:7], 0, v[110:111]
	s_mov_b32 s1, 0x2300000
	v_lshl_add_u64 v[20:21], v[18:19], 0, s[8:9]
	v_add_co_u32_e32 v18, vcc, s1, v18
	global_store_dword v[2:3], v9, off
	s_nop 0
	v_addc_co_u32_e32 v19, vcc, 0, v19, vcc
	s_barrier
; #define LAS __attribute__((address_space(3)))
; #define PIN(x) asm volatile("" : "+v"(x))
; __device__ __forceinline__ unsigned pk2(float lo, float hi) { return pg8::cvt_pk_bf16(lo, hi); }
; __device__ __forceinline__ bf16x8 pack8(f32x4 lo, f32x4 hi) { v4u w; w.x = pk2(lo[0], lo[1]); w.y = pk2(lo[2], lo[3]); w.z = pk2(hi[0], hi[1]); w.w = pk2(hi[2], hi[3]); return __builtin_bit_cast(bf16x8, w); }
; __device__ __forceinline__ void s5_load_consts(S5C& K, const Args& a, int g, int lane) {
;     const int fr = lane & 15, q = lane >> 4;
;     const float* ABAR = (const float*)(a.ws + WS_S5C + S5C_ABAR) + (size_t)g * 128;
;     const bf16* BBAR = (const bf16*)(a.ws + WS_S5C + S5C_BBAR) + (size_t)g * 2048;
; #pragma unroll
;     for (int j = 0; j < 4; ++j) { const f32x4 x0 = *(const f32x4*)(ABAR + 2 * (16 * j + 4 * q)), x1 = *(const f32x4*)(ABAR + 2 * (16 * j + 4 * q) + 4);
;         K.ar[j] = (f32x4){x0[0], x0[2], x1[0], x1[2]}; K.ai[j] = (f32x4){x0[1], x0[3], x1[1], x1[3]}; }
; #pragma unroll
;     for (int mt = 0; mt < 8; ++mt) K.Bf[mt] = *(const v2u*)(BBAR + (mt * 16 + fr) * 16 + 4 * q);
;     const float* cre = a.in[I_CRE] + ((size_t)g * 16 + fr) * 64; const float* cim = a.in[I_CIM] + ((size_t)g * 16 + fr) * 64;
; #pragma unroll
;     for (int j = 0; j < 4; ++j) { const f32x4 r4 = *(const f32x4*)(cre + 16 * j + 4 * q), i4 = *(const f32x4*)(cim + 16 * j + 4 * q); K.Cf[j] = pack8(r4, -i4); }
;     const float* wg = a.in[I_WGLU] + (size_t)g * 512;
;     { f32x4 v, gt;
; #pragma unroll
;       for (int e = 0; e < 4; ++e) { v[e] = wg[(4 * q + e) * 32 + fr]; gt[e] = wg[(4 * q + e) * 32 + 16 + fr]; }
;       K.Wv = (v2u){pk2(v[0], v[1]), pk2(v[2], v[3])}; K.Wg = (v2u){pk2(gt[0], gt[1]), pk2(gt[2], gt[3])}; }
;     K.dsk = *(const f32x4*)(a.in[I_DSKIP] + g * 16 + 4 * q);
;     K.bv = *(const f32x4*)(a.in[I_BGLU] + g * 32 + 4 * q); K.bg = *(const f32x4*)(a.in[I_BGLU] + g * 32 + 16 + 4 * q);
; }
; __device__ __forceinline__ void s5_prompt_task(const Args& a, const Ctx& C, int b, int g, v4u (&xv)[8]) {
;     ...
;     __syncthreads();
; #pragma unroll
;     for (int i = 0; i < 8; ++i) PIN(xv[i]);
; #pragma unroll
;     for (int i = 0; i < 8; ++i) { const int idx = C.tid + 512 * i, tok = idx >> 1; *(LAS v4u*)(XS + tok * 32 + (tok >> 4) * 16 + (idx & 1) * 16) = xv[i]; }
;     S5C K; s5_load_consts(K, a, g, lane);
;     __syncthreads();
	s_waitcnt vmcnt(15)
	s_waitcnt vmcnt(14)
	s_waitcnt vmcnt(13)
	s_waitcnt vmcnt(12)
	s_waitcnt vmcnt(11)
	s_waitcnt vmcnt(10)
	s_waitcnt vmcnt(9)
	s_waitcnt vmcnt(8)
	global_load_dwordx4 v[2:5], v[20:21], off offset:16
	global_load_dwordx4 v[6:9], v[20:21], off offset:144
	global_load_dwordx4 v[10:13], v[20:21], off offset:272
	global_load_dwordx4 v[14:17], v[20:21], off offset:400
	global_load_dwordx4 v[30:33], v[18:19], off
	v_and_b32_e32 v18, 0x1fe0, v94
	v_lshrrev_b32_e32 v19, 1, v0
	v_add_u32_e32 v18, 0, v18
	v_and_b32_e32 v19, 0xf0, v19
	v_and_b32_e32 v24, 16, v94
	v_add3_u32 v18, v18, v19, v24
	ds_write_b128 v18, v[74:77]
	v_and_b32_e32 v18, 0x3fe0, v87
	v_lshrrev_b32_e32 v19, 1, v146
	v_add_u32_e32 v18, 0, v18
	v_and_b32_e32 v19, 0x1f0, v19
	v_add3_u32 v18, v18, v19, v24
	ds_write_b128 v18, v[78:81]
	v_and_b32_e32 v18, 0x7fe0, v148
	v_lshrrev_b32_e32 v19, 1, v147
	v_add_u32_e32 v18, 0, v18
	v_and_b32_e32 v19, 0x3f0, v19
	v_add3_u32 v18, v18, v19, v24
	ds_write_b128 v18, v[70:73]
	v_and_b32_e32 v18, 0x7fe0, v86
	v_lshrrev_b32_e32 v19, 1, v95
	v_add_u32_e32 v18, 0, v18
	v_and_b32_e32 v19, 0x3f0, v19
	v_add3_u32 v18, v18, v19, v24
	ds_write_b128 v18, v[66:69]
	v_and_b32_e32 v18, 0xbfe0, v85
	v_lshrrev_b32_e32 v19, 1, v120
	v_add_u32_e32 v18, 0, v18
	v_and_b32_e32 v19, 0x5f0, v19
	v_add3_u32 v18, v18, v19, v24
	ds_write_b128 v18, v[58:61]
	v_and_b32_e32 v18, 0xffe0, v84
	v_lshrrev_b32_e32 v19, 1, v157
	v_add_u32_e32 v18, 0, v18
	v_and_b32_e32 v19, 0x7f0, v19
	v_add3_u32 v18, v18, v19, v24
	ds_write_b128 v18, v[62:65]
	v_and_b32_e32 v18, 0xffe0, v83
	v_lshrrev_b32_e32 v19, 1, v158
	s_add_u32 s8, s94, s2
	v_add_u32_e32 v18, 0, v18
	v_and_b32_e32 v19, 0x7f0, v19
	s_addc_u32 s9, s95, 0
	v_lshlrev_b32_e32 v110, 1, v112
	v_add3_u32 v25, v18, v19, v24
	v_lshl_add_u64 v[18:19], s[8:9], 0, v[110:111]
	v_lshlrev_b32_e32 v22, 5, v149
	v_mov_b32_e32 v23, v111
	v_lshl_add_u64 v[18:19], v[18:19], 0, v[22:23]
	s_mov_b32 s1, 0x2320000
	v_add_co_u32_e32 v22, vcc, s1, v18
	s_mov_b64 s[8:9], 0x2320000
	s_nop 0
	v_addc_co_u32_e32 v23, vcc, 0, v19, vcc
	global_load_dwordx2 v[114:115], v[22:23], off
	v_lshl_add_u64 v[18:19], v[18:19], 0, s[8:9]
	global_load_dwordx2 v[116:117], v[18:19], off offset:512
	global_load_dwordx4 v[70:73], v[20:21], off offset:128
	v_and_b32_e32 v22, 0xffe0, v82
	v_lshrrev_b32_e32 v23, 1, v155
	global_load_dwordx4 v[74:77], v[20:21], off offset:256
	global_load_dwordx4 v[66:69], v[20:21], off offset:384
	v_add_u32_e32 v22, 0, v22
	v_and_b32_e32 v23, 0x7f0, v23
	v_add3_u32 v22, v22, v23, v24
	ds_write_b128 v25, v[50:53]
	ds_write_b128 v22, v[54:57]
	global_load_dwordx2 v[126:127], v[18:19], off offset:1024
	global_load_dwordx2 v[128:129], v[18:19], off offset:1536
	global_load_dwordx2 v[130:131], v[18:19], off offset:2048
	global_load_dwordx2 v[132:133], v[18:19], off offset:2560
	global_load_dwordx2 v[134:135], v[18:19], off offset:3072
	global_load_dwordx2 v[136:137], v[18:19], off offset:3584
	v_lshl_or_b32 v18, v149, 8, s2
	v_mov_b32_e32 v19, v111
	s_mov_b64 s[16:17], s[24:25]
	v_lshl_add_u64 v[20:21], s[14:15], 0, v[18:19]
	v_lshl_add_u64 v[18:19], s[16:17], 0, v[18:19]
	v_lshlrev_b32_e32 v78, 2, v112
	v_mov_b32_e32 v79, v111
	s_mov_b64 s[20:21], s[28:29]
	v_lshl_add_u64 v[20:21], v[20:21], 0, v[78:79]
	v_lshl_add_u64 v[18:19], v[18:19], 0, v[78:79]
	s_lshl_b32 s1, s0, 11
	global_load_dwordx4 v[58:61], v[20:21], off
	global_load_dwordx4 v[50:53], v[20:21], off offset:64
	global_load_dwordx4 v[62:65], v[18:19], off
	global_load_dwordx4 v[54:57], v[18:19], off offset:64
	global_load_dwordx4 v[42:45], v[20:21], off offset:128
	global_load_dwordx4 v[34:37], v[20:21], off offset:192
	global_load_dwordx4 v[46:49], v[18:19], off offset:128
	global_load_dwordx4 v[38:41], v[18:19], off offset:192
	s_add_u32 s8, s20, s1
	v_lshlrev_b32_e32 v18, 2, v149
	s_mov_b64 s[18:19], s[26:27]
	s_addc_u32 s9, s21, 0
	v_lshl_or_b32 v18, v145, 9, v18
	s_lshl_b32 s1, s0, 4
	s_lshl_b32 s2, s0, 6
	global_load_dword v191, v18, s[8:9]
	global_load_dword v161, v18, s[8:9] offset:64
	global_load_dword v193, v18, s[8:9] offset:128
	global_load_dword v190, v18, s[8:9] offset:192
	global_load_dword v195, v18, s[8:9] offset:256
	global_load_dword v192, v18, s[8:9] offset:320
	global_load_dword v196, v18, s[8:9] offset:384
	global_load_dword v194, v18, s[8:9] offset:448
	s_add_u32 s8, s18, s2
	s_mov_b64 s[22:23], s[30:31]
	s_addc_u32 s9, s19, 0
	s_lshl_b32 s2, s0, 7
	s_add_u32 s10, s22, s2
	s_movk_i32 s2, 0x210
	v_mul_lo_u32 v102, v144, s2
	v_add3_u32 v163, 0, v102, v153
	s_addc_u32 s11, s23, 0
	global_load_dwordx4 v[18:21], v78, s[8:9]
	global_load_dwordx4 v[22:25], v78, s[10:11]
	global_load_dwordx4 v[26:29], v78, s[10:11] offset:64
	s_waitcnt lgkmcnt(0)
	s_barrier
; #define LAS __attribute__((address_space(3)))
; #define S5_UPDATE(K, hre, him, xq) do { const v2u xb_ = (xq); \
;     _Pragma("unroll") for (int j = 0; j < 4; ++j) { const f32x4 cre_ = K.ar[j] * hre[j] - K.ai[j] * him[j], cim_ = K.ar[j] * him[j] + K.ai[j] * hre[j]; \
;         hre[j] = MFMA16K16(K.Bf[2 * j], xb_, cre_); him[j] = MFMA16K16(K.Bf[2 * j + 1], xb_, cim_); } } while (0)
; __device__ __forceinline__ void s5_prompt_task(const Args& a, const Ctx& C, int b, int g, v4u (&xv)[8]) {
;     ...
;     const int chunk = 16 * w + n;
;     f32x4 hre[4], him[4];
; #pragma unroll
;     for (int j = 0; j < 4; ++j) { hre[j] = (f32x4){0.f, 0.f, 0.f, 0.f}; him[j] = (f32x4){0.f, 0.f, 0.f, 0.f}; }
;     const LAS unsigned char* xsl = XS + chunk * 528 + q * 8;
;     for (int t = 0; t < 16; ++t) { const v2u xq = *(const LAS v2u*)(xsl + t * 32); S5_UPDATE(K, hre, him, xq); }
	ds_read2_b64 v[104:107], v163 offset1:4
	s_waitcnt vmcnt(30)
	v_mov_b32_e32 v78, v30
	v_mov_b32_e32 v79, v32
	v_mov_b32_e32 v80, v2
	v_mov_b32_e32 v81, v4
	v_pk_mul_f32 v[86:87], v[78:79], 0 op_sel_hi:[1,0]
	v_pk_mul_f32 v[90:91], v[80:81], 0 op_sel_hi:[1,0]
	v_xor_b32_e32 v83, 0x80000000, v33
	v_xor_b32_e32 v82, 0x80000000, v31
	v_xor_b32_e32 v85, 0x80000000, v5
	v_xor_b32_e32 v84, 0x80000000, v3
	v_mov_b32_e32 v118, v3
	v_pk_fma_f32 v[82:83], v[82:83], 0, v[86:87] op_sel_hi:[1,0,1]
	v_pk_fma_f32 v[84:85], v[84:85], 0, v[90:91] op_sel_hi:[1,0,1]
	v_mov_b32_e32 v88, v31
	v_mov_b32_e32 v89, v33
	v_mov_b32_e32 v119, v5
	s_waitcnt vmcnt(29) lgkmcnt(0)
	v_mfma_f32_16x16x16_bf16 v[138:141], v[114:115], v[104:105], v[82:85]
	s_nop 2
	v_fma_f32 v82, v88, 0, v86
	v_fma_f32 v83, v89, 0, v87
	v_pk_fma_f32 v[84:85], v[118:119], 0, v[90:91] op_sel_hi:[1,0,1]
	v_mov_b32_e32 v86, v6
	v_mov_b32_e32 v87, v8
	s_waitcnt vmcnt(28)
	v_mfma_f32_16x16x16_bf16 v[146:149], v[116:117], v[104:105], v[82:85]
	v_mul_f32_e64 v94, v86, 0
	v_mul_f32_e64 v95, v87, 0
	v_xor_b32_e32 v91, 0x80000000, v9
	v_xor_b32_e32 v90, 0x80000000, v7
	s_waitcnt vmcnt(27)
	v_mov_b32_e32 v82, v70
	v_mov_b32_e32 v83, v72
	v_mov_b32_e32 v120, v7
	v_pk_mul_f32 v[84:85], v[82:83], 0 op_sel_hi:[1,0]
	v_pk_fma_f32 v[92:93], v[90:91], 0, v[94:95] op_sel_hi:[1,0,1]
	v_xor_b32_e32 v91, 0x80000000, v73
	v_xor_b32_e32 v90, 0x80000000, v71
	v_mov_b32_e32 v121, v9
	v_pk_fma_f32 v[90:91], v[90:91], 0, v[84:85] op_sel_hi:[1,0,1]
	v_pk_fma_f32 v[98:99], v[120:121], 0, v[94:95] op_sel_hi:[1,0,1]
	v_mov_b32_e32 v94, v71
	v_mov_b32_e32 v95, v73
	s_waitcnt vmcnt(24)
	v_mfma_f32_16x16x16_bf16 v[150:153], v[126:127], v[104:105], v[90:93]
	v_fma_f32 v96, v94, 0, v84
	v_fma_f32 v97, v95, 0, v85
	v_mov_b32_e32 v84, v74
	v_mov_b32_e32 v85, v76
	v_mov_b32_e32 v92, v10
	v_mov_b32_e32 v93, v12
	s_waitcnt vmcnt(23)
	v_mfma_f32_16x16x16_bf16 v[154:157], v[128:129], v[104:105], v[96:99]
	v_mul_f32_e64 v100, v92, 0
	v_mul_f32_e64 v101, v93, 0
	v_pk_mul_f32 v[90:91], v[84:85], 0 op_sel_hi:[1,0]
	v_mov_b32_e32 v122, v11
	v_xor_b32_e32 v97, 0x80000000, v13
	v_xor_b32_e32 v96, 0x80000000, v11
	v_pk_fma_f32 v[98:99], v[96:97], 0, v[100:101] op_sel_hi:[1,0,1]
	v_xor_b32_e32 v97, 0x80000000, v77
	v_xor_b32_e32 v96, 0x80000000, v75
	v_pk_fma_f32 v[96:97], v[96:97], 0, v[90:91] op_sel_hi:[1,0,1]
	v_mov_b32_e32 v123, v13
	v_pk_fma_f32 v[166:167], v[122:123], 0, v[100:101] op_sel_hi:[1,0,1]
	s_waitcnt vmcnt(22)
	v_mfma_f32_16x16x16_bf16 v[168:171], v[130:131], v[104:105], v[96:99]
	v_xor_b32_e32 v143, 0x80000000, v17
	v_xor_b32_e32 v142, 0x80000000, v15
	v_mov_b32_e32 v124, v15
	v_mov_b32_e32 v98, v75
	v_mov_b32_e32 v99, v77
	v_mov_b32_e32 v96, v14
	v_mov_b32_e32 v97, v16
	v_pk_fma_f32 v[164:165], v[98:99], 0, v[90:91] op_sel_hi:[1,0,1]
	v_mov_b32_e32 v90, v66
	v_mov_b32_e32 v91, v68
	v_pk_mul_f32 v[100:101], v[96:97], 0 op_sel_hi:[1,0]
	v_pk_mul_f32 v[108:109], v[90:91], 0 op_sel_hi:[1,0]
	v_pk_fma_f32 v[174:175], v[142:143], 0, v[100:101] op_sel_hi:[1,0,1]
	v_xor_b32_e32 v143, 0x80000000, v69
	v_xor_b32_e32 v142, 0x80000000, v67
	v_mov_b32_e32 v125, v17
	v_pk_fma_f32 v[172:173], v[142:143], 0, v[108:109] op_sel_hi:[1,0,1]
	v_pk_fma_f32 v[176:177], v[124:125], 0, v[100:101] op_sel_hi:[1,0,1]
	v_mov_b32_e32 v100, v67
	v_mov_b32_e32 v101, v69
	s_waitcnt vmcnt(20)
	v_mfma_f32_16x16x16_bf16 v[178:181], v[134:135], v[104:105], v[172:175]
	s_add_i32 s8, 0, 0x10800
	v_add_u32_e32 v3, s8, v102
	v_lshlrev_b32_e32 v7, 5, v145
	v_pk_fma_f32 v[174:175], v[100:101], 0, v[108:109] op_sel_hi:[1,0,1]
	v_mfma_f32_16x16x16_bf16 v[164:167], v[132:133], v[104:105], v[164:167]
	v_mul_f32_e64 v108, v88, v146
	v_mul_f32_e64 v109, v89, v147
	v_add_u32_e32 v3, v3, v7
	v_pk_fma_f32 v[182:183], v[78:79], v[138:139], v[108:109] neg_lo:[0,0,1] neg_hi:[0,0,1]
	s_waitcnt vmcnt(19)
	v_mfma_f32_16x16x16_bf16 v[172:175], v[136:137], v[104:105], v[174:177]
	v_mul_f32_e64 v104, v118, v148
	v_mul_f32_e64 v105, v119, v149
	v_pk_mul_f32 v[108:109], v[78:79], v[146:147]
	v_pk_fma_f32 v[184:185], v[80:81], v[140:141], v[104:105] neg_lo:[0,0,1] neg_hi:[0,0,1]
	v_pk_mul_f32 v[104:105], v[80:81], v[148:149]
	v_pk_fma_f32 v[138:139], v[88:89], v[138:139], v[108:109]
	v_pk_fma_f32 v[140:141], v[118:119], v[140:141], v[104:105]
	v_pk_mul_f32 v[104:105], v[120:121], v[156:157]
	v_pk_mul_f32 v[108:109], v[94:95], v[154:155]
	v_pk_fma_f32 v[148:149], v[86:87], v[152:153], v[104:105] neg_lo:[0,0,1] neg_hi:[0,0,1]
	v_pk_fma_f32 v[146:147], v[82:83], v[150:151], v[108:109] neg_lo:[0,0,1] neg_hi:[0,0,1]
	v_pk_mul_f32 v[104:105], v[86:87], v[156:157]
	v_pk_mul_f32 v[108:109], v[82:83], v[154:155]
	v_pk_fma_f32 v[152:153], v[120:121], v[152:153], v[104:105]
	v_pk_fma_f32 v[150:151], v[94:95], v[150:151], v[108:109]
	v_pk_mul_f32 v[104:105], v[122:123], v[166:167]
	v_pk_mul_f32 v[108:109], v[98:99], v[164:165]
	v_pk_fma_f32 v[156:157], v[92:93], v[170:171], v[104:105] neg_lo:[0,0,1] neg_hi:[0,0,1]
	v_pk_fma_f32 v[154:155], v[84:85], v[168:169], v[108:109] neg_lo:[0,0,1] neg_hi:[0,0,1]
	v_pk_mul_f32 v[104:105], v[92:93], v[166:167]
	v_pk_mul_f32 v[108:109], v[84:85], v[164:165]
	v_pk_fma_f32 v[166:167], v[122:123], v[170:171], v[104:105]
	v_pk_fma_f32 v[164:165], v[98:99], v[168:169], v[108:109]
	v_pk_mul_f32 v[104:105], v[124:125], v[174:175]
	v_pk_mul_f32 v[108:109], v[100:101], v[172:173]
	v_pk_fma_f32 v[170:171], v[96:97], v[180:181], v[104:105] neg_lo:[0,0,1] neg_hi:[0,0,1]
	v_pk_fma_f32 v[168:169], v[90:91], v[178:179], v[108:109] neg_lo:[0,0,1] neg_hi:[0,0,1]
	v_pk_mul_f32 v[104:105], v[96:97], v[174:175]
	v_pk_mul_f32 v[108:109], v[90:91], v[172:173]
	v_mfma_f32_16x16x16_bf16 v[138:141], v[116:117], v[106:107], v[138:141]
	v_fma_f32 v174, v124, v180, v104
	v_fma_f32 v175, v125, v181, v105
	v_pk_fma_f32 v[172:173], v[100:101], v[178:179], v[108:109]
	s_add_u32 s4, s94, s4
	v_mfma_f32_16x16x16_bf16 v[182:185], v[114:115], v[106:107], v[182:185]
	s_addc_u32 s5, s95, s5
	s_nop 1
	v_pk_mul_f32 v[108:109], v[118:119], v[140:141]
	v_pk_mul_f32 v[142:143], v[88:89], v[138:139]
	v_mfma_f32_16x16x16_bf16 v[146:149], v[126:127], v[106:107], v[146:149]
	v_mul_f32_e64 v138, v78, v138
	v_mul_f32_e64 v139, v79, v139
	v_pk_fma_f32 v[178:179], v[80:81], v[184:185], v[108:109] neg_lo:[0,0,1] neg_hi:[0,0,1]
	v_pk_fma_f32 v[176:177], v[78:79], v[182:183], v[142:143] neg_lo:[0,0,1] neg_hi:[0,0,1]
	v_mfma_f32_16x16x16_bf16 v[150:153], v[128:129], v[106:107], v[150:153]
	v_mul_f32_e64 v108, v80, v140
	v_mul_f32_e64 v109, v81, v141
	v_lshlrev_b32_e32 v7, 4, v144
	s_mov_b32 s2, 0x2308000
	v_mfma_f32_16x16x16_bf16 v[154:157], v[130:131], v[106:107], v[154:157]
	v_mov_b32_e32 v160, v111
	v_mfma_f32_16x16x16_bf16 v[164:167], v[132:133], v[106:107], v[164:167]
	v_mfma_f32_16x16x16_bf16 v[168:171], v[134:135], v[106:107], v[168:171]
	v_mfma_f32_16x16x16_bf16 v[104:107], v[136:137], v[106:107], v[172:175]
	s_nop 2
	ds_read2_b64 v[172:175], v163 offset0:8 offset1:12
	s_waitcnt lgkmcnt(0)
; #define LAS __attribute__((address_space(3)))
; #define S5_UPDATE(K, hre, him, xq) do { const v2u xb_ = (xq); \
;     _Pragma("unroll") for (int j = 0; j < 4; ++j) { const f32x4 cre_ = K.ar[j] * hre[j] - K.ai[j] * him[j], cim_ = K.ar[j] * him[j] + K.ai[j] * hre[j]; \
;         hre[j] = MFMA16K16(K.Bf[2 * j], xb_, cre_); him[j] = MFMA16K16(K.Bf[2 * j + 1], xb_, cim_); } } while (0)
; __device__ __forceinline__ void s5_prompt_task(const Args& a, const Ctx& C, int b, int g, v4u (&xv)[8]) {
;     ...
;     const int chunk = 16 * w + n;
;     f32x4 hre[4], him[4];
; #pragma unroll
;     for (int j = 0; j < 4; ++j) { hre[j] = (f32x4){0.f, 0.f, 0.f, 0.f}; him[j] = (f32x4){0.f, 0.f, 0.f, 0.f}; }
;     const LAS unsigned char* xsl = XS + chunk * 528 + q * 8;
;     for (int t = 0; t < 16; ++t) { const v2u xq = *(const LAS v2u*)(xsl + t * 32); S5_UPDATE(K, hre, him, xq); }
	v_mfma_f32_16x16x16_bf16 v[140:143], v[114:115], v[172:173], v[176:179]
	s_nop 2
	v_fma_f32 v178, v118, v184, v108
	v_fma_f32 v179, v119, v185, v109
	v_pk_fma_f32 v[176:177], v[88:89], v[182:183], v[138:139]
	v_pk_mul_f32 v[108:109], v[120:121], v[152:153]
	v_pk_mul_f32 v[138:139], v[94:95], v[150:151]
	v_pk_fma_f32 v[182:183], v[86:87], v[148:149], v[108:109] neg_lo:[0,0,1] neg_hi:[0,0,1]
	v_pk_fma_f32 v[180:181], v[82:83], v[146:147], v[138:139] neg_lo:[0,0,1] neg_hi:[0,0,1]
	v_pk_mul_f32 v[108:109], v[86:87], v[152:153]
	v_pk_mul_f32 v[138:139], v[82:83], v[150:151]
	v_mfma_f32_16x16x16_bf16 v[176:179], v[116:117], v[172:173], v[176:179]
	v_fma_f32 v148, v120, v148, v108
	v_fma_f32 v149, v121, v149, v109
	v_pk_fma_f32 v[146:147], v[94:95], v[146:147], v[138:139]
	v_pk_mul_f32 v[108:109], v[122:123], v[166:167]
	v_pk_mul_f32 v[138:139], v[98:99], v[164:165]
	v_pk_fma_f32 v[152:153], v[92:93], v[156:157], v[108:109] neg_lo:[0,0,1] neg_hi:[0,0,1]
	v_pk_fma_f32 v[150:151], v[84:85], v[154:155], v[138:139] neg_lo:[0,0,1] neg_hi:[0,0,1]
	v_pk_mul_f32 v[108:109], v[92:93], v[166:167]
	v_pk_mul_f32 v[138:139], v[84:85], v[164:165]
	v_pk_fma_f32 v[156:157], v[122:123], v[156:157], v[108:109]
	v_pk_fma_f32 v[154:155], v[98:99], v[154:155], v[138:139]
	v_pk_mul_f32 v[108:109], v[124:125], v[106:107]
	v_pk_mul_f32 v[138:139], v[100:101], v[104:105]
	v_mfma_f32_16x16x16_bf16 v[146:149], v[128:129], v[172:173], v[146:149]
	v_fma_f32 v166, v96, v170, -v108
	v_fma_f32 v167, v97, v171, -v109
	v_pk_fma_f32 v[164:165], v[90:91], v[168:169], v[138:139] neg_lo:[0,0,1] neg_hi:[0,0,1]
	v_pk_mul_f32 v[138:139], v[96:97], v[106:107]
	v_pk_mul_f32 v[104:105], v[90:91], v[104:105]
	v_mfma_f32_16x16x16_bf16 v[180:183], v[126:127], v[172:173], v[180:183]
	v_mfma_f32_16x16x16_bf16 v[106:109], v[134:135], v[172:173], v[164:167]
	s_nop 2
	v_fma_f32 v166, v124, v170, v138
	v_fma_f32 v167, v125, v171, v139
	v_pk_fma_f32 v[164:165], v[100:101], v[168:169], v[104:105]
	v_pk_mul_f32 v[104:105], v[118:119], v[178:179]
	v_pk_mul_f32 v[138:139], v[88:89], v[176:177]
	v_mfma_f32_16x16x16_bf16 v[154:157], v[132:133], v[172:173], v[154:157]
	v_fma_f32 v170, v80, v142, -v104
	v_fma_f32 v171, v81, v143, -v105
	v_pk_fma_f32 v[168:169], v[78:79], v[140:141], v[138:139] neg_lo:[0,0,1] neg_hi:[0,0,1]
	v_pk_mul_f32 v[104:105], v[80:81], v[178:179]
	v_pk_mul_f32 v[138:139], v[78:79], v[176:177]
	v_mfma_f32_16x16x16_bf16 v[150:153], v[130:131], v[172:173], v[150:153]
	v_fma_f32 v142, v118, v142, v104
	v_fma_f32 v143, v119, v143, v105
	v_pk_fma_f32 v[140:141], v[88:89], v[140:141], v[138:139]
	v_pk_mul_f32 v[104:105], v[120:121], v[148:149]
	v_mfma_f32_16x16x16_bf16 v[164:167], v[136:137], v[172:173], v[164:167]
	v_fma_f32 v178, v86, v182, -v104
	v_fma_f32 v179, v87, v183, -v105
	v_pk_mul_f32 v[104:105], v[86:87], v[148:149]
	v_mfma_f32_16x16x16_bf16 v[138:141], v[116:117], v[174:175], v[140:143]
	v_fma_f32 v148, v120, v182, v104
	v_fma_f32 v149, v121, v183, v105
	v_pk_mul_f32 v[104:105], v[122:123], v[156:157]
	v_pk_mul_f32 v[142:143], v[94:95], v[146:147]
	v_pk_fma_f32 v[182:183], v[92:93], v[152:153], v[104:105] neg_lo:[0,0,1] neg_hi:[0,0,1]
	v_pk_fma_f32 v[176:177], v[82:83], v[180:181], v[142:143] neg_lo:[0,0,1] neg_hi:[0,0,1]
	v_pk_mul_f32 v[142:143], v[82:83], v[146:147]
	v_pk_mul_f32 v[104:105], v[92:93], v[156:157]
	v_pk_fma_f32 v[146:147], v[94:95], v[180:181], v[142:143]
	v_pk_mul_f32 v[142:143], v[98:99], v[154:155]
	v_mfma_f32_16x16x16_bf16 v[168:171], v[114:115], v[174:175], v[168:171]
	v_fma_f32 v180, v84, v150, -v142
	v_fma_f32 v181, v85, v151, -v143
	v_pk_mul_f32 v[142:143], v[84:85], v[154:155]
	v_pk_fma_f32 v[152:153], v[122:123], v[152:153], v[104:105]
	v_pk_fma_f32 v[150:151], v[98:99], v[150:151], v[142:143]
	v_pk_mul_f32 v[104:105], v[124:125], v[166:167]
	v_pk_mul_f32 v[142:143], v[100:101], v[164:165]
	v_mfma_f32_16x16x16_bf16 v[146:149], v[128:129], v[174:175], v[146:149]
	v_mfma_f32_16x16x16_bf16 v[156:159], v[130:131], v[174:175], v[180:183]
	s_nop 2
	v_fma_f32 v182, v96, v108, -v104
	v_fma_f32 v183, v97, v109, -v105
	v_pk_fma_f32 v[180:181], v[90:91], v[106:107], v[142:143] neg_lo:[0,0,1] neg_hi:[0,0,1]
	v_pk_mul_f32 v[104:105], v[96:97], v[166:167]
	v_pk_mul_f32 v[142:143], v[90:91], v[164:165]
	ds_read2_b64 v[164:167], v163 offset0:16 offset1:20
	v_mfma_f32_16x16x16_bf16 v[176:179], v[126:127], v[174:175], v[176:179]
	v_fma_f32 v108, v124, v108, v104
	v_fma_f32 v109, v125, v109, v105
	v_pk_fma_f32 v[106:107], v[100:101], v[106:107], v[142:143]
	v_pk_mul_f32 v[142:143], v[88:89], v[138:139]
	v_mfma_f32_16x16x16_bf16 v[150:153], v[132:133], v[174:175], v[150:153]
	v_mul_f32_e64 v138, v78, v138
	v_mul_f32_e64 v139, v79, v139
	v_pk_fma_f32 v[172:173], v[78:79], v[168:169], v[142:143] neg_lo:[0,0,1] neg_hi:[0,0,1]
	v_pk_fma_f32 v[168:169], v[88:89], v[168:169], v[138:139]
	v_mfma_f32_16x16x16_bf16 v[104:107], v[136:137], v[174:175], v[106:109]
	v_mul_f32_e64 v138, v94, v146
	v_mul_f32_e64 v139, v95, v147
	s_nop 0
	v_pk_mul_f32 v[108:109], v[118:119], v[140:141]
	v_mfma_f32_16x16x16_bf16 v[180:183], v[134:135], v[174:175], v[180:183]
	v_fma_f32 v174, v80, v170, -v108
	v_fma_f32 v175, v81, v171, -v109
	v_pk_mul_f32 v[108:109], v[80:81], v[140:141]
	s_nop 0
	v_pk_fma_f32 v[170:171], v[118:119], v[170:171], v[108:109]
	v_pk_mul_f32 v[108:109], v[120:121], v[148:149]
	s_waitcnt lgkmcnt(0)
; #define LAS __attribute__((address_space(3)))
; #define S5_UPDATE(K, hre, him, xq) do { const v2u xb_ = (xq); \
;     _Pragma("unroll") for (int j = 0; j < 4; ++j) { const f32x4 cre_ = K.ar[j] * hre[j] - K.ai[j] * him[j], cim_ = K.ar[j] * him[j] + K.ai[j] * hre[j]; \
;         hre[j] = MFMA16K16(K.Bf[2 * j], xb_, cre_); him[j] = MFMA16K16(K.Bf[2 * j + 1], xb_, cim_); } } while (0)
; __device__ __forceinline__ void s5_prompt_task(const Args& a, const Ctx& C, int b, int g, v4u (&xv)[8]) {
;     ...
;     const int chunk = 16 * w + n;
;     f32x4 hre[4], him[4];
; #pragma unroll
;     for (int j = 0; j < 4; ++j) { hre[j] = (f32x4){0.f, 0.f, 0.f, 0.f}; him[j] = (f32x4){0.f, 0.f, 0.f, 0.f}; }
;     const LAS unsigned char* xsl = XS + chunk * 528 + q * 8;
;     for (int t = 0; t < 16; ++t) { const v2u xq = *(const LAS v2u*)(xsl + t * 32); S5_UPDATE(K, hre, him, xq); }
	v_mfma_f32_16x16x16_bf16 v[140:143], v[114:115], v[164:165], v[172:175]
	s_nop 2
	v_fma_f32 v174, v86, v178, -v108
	v_fma_f32 v175, v87, v179, -v109
	v_pk_fma_f32 v[172:173], v[82:83], v[176:177], v[138:139] neg_lo:[0,0,1] neg_hi:[0,0,1]
	v_pk_mul_f32 v[108:109], v[86:87], v[148:149]
	v_pk_mul_f32 v[138:139], v[82:83], v[146:147]
	v_mfma_f32_16x16x16_bf16 v[168:171], v[116:117], v[164:165], v[168:171]
	v_fma_f32 v148, v120, v178, v108
	v_fma_f32 v149, v121, v179, v109
	v_pk_fma_f32 v[146:147], v[94:95], v[176:177], v[138:139]
	v_pk_mul_f32 v[108:109], v[122:123], v[152:153]
	v_pk_mul_f32 v[138:139], v[98:99], v[150:151]
	v_pk_fma_f32 v[178:179], v[92:93], v[158:159], v[108:109] neg_lo:[0,0,1] neg_hi:[0,0,1]
	v_pk_fma_f32 v[176:177], v[84:85], v[156:157], v[138:139] neg_lo:[0,0,1] neg_hi:[0,0,1]
	v_pk_mul_f32 v[108:109], v[92:93], v[152:153]
	v_pk_mul_f32 v[138:139], v[84:85], v[150:151]
	v_pk_fma_f32 v[158:159], v[122:123], v[158:159], v[108:109]
	v_pk_fma_f32 v[156:157], v[98:99], v[156:157], v[138:139]
	v_pk_mul_f32 v[108:109], v[124:125], v[106:107]
	v_pk_mul_f32 v[138:139], v[100:101], v[104:105]
	v_mfma_f32_16x16x16_bf16 v[146:149], v[128:129], v[164:165], v[146:149]
	v_mul_f32_e64 v104, v90, v104
	v_mul_f32_e64 v105, v91, v105
	v_mfma_f32_16x16x16_bf16 v[152:155], v[130:131], v[164:165], v[176:179]
	s_nop 2
	v_fma_f32 v178, v96, v182, -v108
	v_fma_f32 v179, v97, v183, -v109
	v_pk_fma_f32 v[176:177], v[90:91], v[180:181], v[138:139] neg_lo:[0,0,1] neg_hi:[0,0,1]
	v_pk_mul_f32 v[138:139], v[96:97], v[106:107]
	v_mfma_f32_16x16x16_bf16 v[172:175], v[126:127], v[164:165], v[172:175]
	v_mfma_f32_16x16x16_bf16 v[106:109], v[134:135], v[164:165], v[176:179]
	s_nop 2
	v_fma_f32 v178, v124, v182, v138
	v_fma_f32 v179, v125, v183, v139
	v_pk_fma_f32 v[176:177], v[100:101], v[180:181], v[104:105]
	v_pk_mul_f32 v[104:105], v[118:119], v[170:171]
	v_pk_mul_f32 v[138:139], v[88:89], v[168:169]
	v_mfma_f32_16x16x16_bf16 v[156:159], v[132:133], v[164:165], v[156:159]
	v_fma_f32 v182, v80, v142, -v104
	v_fma_f32 v183, v81, v143, -v105
	v_pk_fma_f32 v[180:181], v[78:79], v[140:141], v[138:139] neg_lo:[0,0,1] neg_hi:[0,0,1]
	v_pk_mul_f32 v[104:105], v[80:81], v[170:171]
	v_pk_mul_f32 v[138:139], v[78:79], v[168:169]
	v_pk_fma_f32 v[142:143], v[118:119], v[142:143], v[104:105]
	v_pk_fma_f32 v[140:141], v[88:89], v[140:141], v[138:139]
	v_mfma_f32_16x16x16_bf16 v[176:179], v[136:137], v[164:165], v[176:179]
	v_mul_f32_e64 v104, v120, v148
	v_mul_f32_e64 v105, v121, v149
	v_pk_fma_f32 v[170:171], v[86:87], v[174:175], v[104:105] neg_lo:[0,0,1] neg_hi:[0,0,1]
	v_mfma_f32_16x16x16_bf16 v[138:141], v[116:117], v[166:167], v[140:143]
	v_mul_f32_e64 v104, v86, v148
	v_mul_f32_e64 v105, v87, v149
	s_nop 0
	v_pk_mul_f32 v[142:143], v[94:95], v[146:147]
	v_mfma_f32_16x16x16_bf16 v[180:183], v[114:115], v[166:167], v[180:183]
	v_fma_f32 v168, v82, v172, -v142
	v_fma_f32 v169, v83, v173, -v143
	v_pk_mul_f32 v[142:143], v[82:83], v[146:147]
	s_nop 0
	v_mfma_f32_16x16x16_bf16 v[148:151], v[126:127], v[166:167], v[168:171]
	s_nop 2
	v_fma_f32 v170, v120, v174, v104
	v_fma_f32 v171, v121, v175, v105
	v_pk_fma_f32 v[168:169], v[94:95], v[172:173], v[142:143]
	v_pk_mul_f32 v[104:105], v[122:123], v[158:159]
	v_pk_mul_f32 v[142:143], v[98:99], v[156:157]
	v_pk_fma_f32 v[174:175], v[92:93], v[154:155], v[104:105] neg_lo:[0,0,1] neg_hi:[0,0,1]
	v_pk_fma_f32 v[172:173], v[84:85], v[152:153], v[142:143] neg_lo:[0,0,1] neg_hi:[0,0,1]
	v_pk_mul_f32 v[104:105], v[92:93], v[158:159]
	v_pk_mul_f32 v[142:143], v[84:85], v[156:157]
	v_pk_fma_f32 v[154:155], v[122:123], v[154:155], v[104:105]
	v_pk_fma_f32 v[152:153], v[98:99], v[152:153], v[142:143]
	v_pk_mul_f32 v[104:105], v[124:125], v[178:179]
	v_pk_mul_f32 v[142:143], v[100:101], v[176:177]
	v_pk_fma_f32 v[158:159], v[96:97], v[108:109], v[104:105] neg_lo:[0,0,1] neg_hi:[0,0,1]
	v_pk_fma_f32 v[156:157], v[90:91], v[106:107], v[142:143] neg_lo:[0,0,1] neg_hi:[0,0,1]
	v_pk_mul_f32 v[104:105], v[96:97], v[178:179]
	v_pk_mul_f32 v[142:143], v[90:91], v[176:177]
	v_pk_fma_f32 v[108:109], v[124:125], v[108:109], v[104:105]
	v_pk_fma_f32 v[106:107], v[100:101], v[106:107], v[142:143]
	v_mfma_f32_16x16x16_bf16 v[168:171], v[128:129], v[166:167], v[168:171]
	v_mul_f32_e64 v142, v88, v138
	v_mul_f32_e64 v143, v89, v139
	v_pk_mul_f32 v[138:139], v[78:79], v[138:139]
	v_pk_fma_f32 v[176:177], v[78:79], v[180:181], v[142:143] neg_lo:[0,0,1] neg_hi:[0,0,1]
	v_mfma_f32_16x16x16_bf16 v[172:175], v[130:131], v[166:167], v[172:175]
	v_mfma_f32_16x16x16_bf16 v[152:155], v[132:133], v[166:167], v[152:155]
	v_mfma_f32_16x16x16_bf16 v[156:159], v[134:135], v[166:167], v[156:159]
	v_mfma_f32_16x16x16_bf16 v[104:107], v[136:137], v[166:167], v[106:109]
	ds_read2_b64 v[164:167], v163 offset0:24 offset1:28
	s_nop 1
	v_pk_mul_f32 v[108:109], v[118:119], v[140:141]
	s_nop 0
	v_pk_fma_f32 v[178:179], v[80:81], v[182:183], v[108:109] neg_lo:[0,0,1] neg_hi:[0,0,1]
	v_pk_mul_f32 v[108:109], v[80:81], v[140:141]
	s_waitcnt lgkmcnt(0)
; #define LAS __attribute__((address_space(3)))
; #define S5_UPDATE(K, hre, him, xq) do { const v2u xb_ = (xq); \
;     _Pragma("unroll") for (int j = 0; j < 4; ++j) { const f32x4 cre_ = K.ar[j] * hre[j] - K.ai[j] * him[j], cim_ = K.ar[j] * him[j] + K.ai[j] * hre[j]; \
;         hre[j] = MFMA16K16(K.Bf[2 * j], xb_, cre_); him[j] = MFMA16K16(K.Bf[2 * j + 1], xb_, cim_); } } while (0)
; __device__ __forceinline__ void s5_prompt_task(const Args& a, const Ctx& C, int b, int g, v4u (&xv)[8]) {
;     ...
;     const int chunk = 16 * w + n;
;     f32x4 hre[4], him[4];
; #pragma unroll
;     for (int j = 0; j < 4; ++j) { hre[j] = (f32x4){0.f, 0.f, 0.f, 0.f}; him[j] = (f32x4){0.f, 0.f, 0.f, 0.f}; }
;     const LAS unsigned char* xsl = XS + chunk * 528 + q * 8;
;     for (int t = 0; t < 16; ++t) { const v2u xq = *(const LAS v2u*)(xsl + t * 32); S5_UPDATE(K, hre, him, xq); }
	v_mfma_f32_16x16x16_bf16 v[140:143], v[114:115], v[164:165], v[176:179]
	s_nop 2
	v_fma_f32 v176, v88, v180, v138
	v_fma_f32 v177, v89, v181, v139
	v_pk_mul_f32 v[138:139], v[94:95], v[168:169]
	v_pk_fma_f32 v[178:179], v[118:119], v[182:183], v[108:109]
	v_pk_mul_f32 v[108:109], v[120:121], v[170:171]
	v_pk_fma_f32 v[180:181], v[82:83], v[148:149], v[138:139] neg_lo:[0,0,1] neg_hi:[0,0,1]
	v_pk_mul_f32 v[138:139], v[82:83], v[168:169]
	v_mfma_f32_16x16x16_bf16 v[176:179], v[116:117], v[164:165], v[176:179]
	v_fma_f32 v182, v86, v150, -v108
	v_fma_f32 v183, v87, v151, -v109
	v_pk_mul_f32 v[108:109], v[86:87], v[170:171]
	v_pk_fma_f32 v[148:149], v[94:95], v[148:149], v[138:139]
	v_pk_mul_f32 v[138:139], v[98:99], v[152:153]
	v_pk_fma_f32 v[150:151], v[120:121], v[150:151], v[108:109]
	v_pk_mul_f32 v[108:109], v[122:123], v[154:155]
	v_pk_fma_f32 v[168:169], v[84:85], v[172:173], v[138:139] neg_lo:[0,0,1] neg_hi:[0,0,1]
	v_pk_mul_f32 v[138:139], v[84:85], v[152:153]
	v_mfma_f32_16x16x16_bf16 v[146:149], v[128:129], v[164:165], v[148:151]
	v_fma_f32 v170, v92, v174, -v108
	v_fma_f32 v171, v93, v175, -v109
	v_pk_mul_f32 v[108:109], v[92:93], v[154:155]
	v_pk_fma_f32 v[150:151], v[98:99], v[172:173], v[138:139]
	v_pk_mul_f32 v[138:139], v[100:101], v[104:105]
	v_pk_fma_f32 v[152:153], v[122:123], v[174:175], v[108:109]
	v_pk_mul_f32 v[108:109], v[124:125], v[106:107]
	v_pk_fma_f32 v[172:173], v[90:91], v[156:157], v[138:139] neg_lo:[0,0,1] neg_hi:[0,0,1]
	v_pk_mul_f32 v[138:139], v[96:97], v[106:107]
	v_pk_mul_f32 v[104:105], v[90:91], v[104:105]
	v_mfma_f32_16x16x16_bf16 v[180:183], v[126:127], v[164:165], v[180:183]
	v_fma_f32 v174, v96, v158, -v108
	v_fma_f32 v175, v97, v159, -v109
	v_pk_fma_f32 v[158:159], v[124:125], v[158:159], v[138:139]
	v_pk_fma_f32 v[156:157], v[100:101], v[156:157], v[104:105]
	v_pk_mul_f32 v[104:105], v[118:119], v[178:179]
	v_pk_mul_f32 v[138:139], v[88:89], v[176:177]
	v_mfma_f32_16x16x16_bf16 v[150:153], v[132:133], v[164:165], v[150:153]
	v_mfma_f32_16x16x16_bf16 v[106:109], v[134:135], v[164:165], v[172:175]
	s_nop 2
	v_fma_f32 v174, v80, v142, -v104
	v_fma_f32 v175, v81, v143, -v105
	v_pk_fma_f32 v[172:173], v[78:79], v[140:141], v[138:139] neg_lo:[0,0,1] neg_hi:[0,0,1]
	v_pk_mul_f32 v[104:105], v[80:81], v[178:179]
	v_pk_mul_f32 v[138:139], v[78:79], v[176:177]
	v_mfma_f32_16x16x16_bf16 v[168:171], v[130:131], v[164:165], v[168:171]
	v_fma_f32 v142, v118, v142, v104
	v_fma_f32 v143, v119, v143, v105
	v_pk_fma_f32 v[140:141], v[88:89], v[140:141], v[138:139]
	v_pk_mul_f32 v[104:105], v[120:121], v[148:149]
	v_mfma_f32_16x16x16_bf16 v[154:157], v[136:137], v[164:165], v[156:159]
	v_fma_f32 v178, v86, v182, -v104
	v_fma_f32 v179, v87, v183, -v105
	v_pk_mul_f32 v[104:105], v[86:87], v[148:149]
	v_mfma_f32_16x16x16_bf16 v[138:141], v[116:117], v[166:167], v[140:143]
	v_fma_f32 v148, v120, v182, v104
	v_fma_f32 v149, v121, v183, v105
	v_pk_mul_f32 v[104:105], v[122:123], v[152:153]
	v_pk_mul_f32 v[142:143], v[94:95], v[146:147]
	v_pk_fma_f32 v[182:183], v[92:93], v[170:171], v[104:105] neg_lo:[0,0,1] neg_hi:[0,0,1]
	v_pk_fma_f32 v[176:177], v[82:83], v[180:181], v[142:143] neg_lo:[0,0,1] neg_hi:[0,0,1]
	v_pk_mul_f32 v[142:143], v[82:83], v[146:147]
	v_pk_mul_f32 v[104:105], v[92:93], v[152:153]
	v_pk_fma_f32 v[146:147], v[94:95], v[180:181], v[142:143]
	v_pk_mul_f32 v[142:143], v[98:99], v[150:151]
	v_pk_fma_f32 v[152:153], v[122:123], v[170:171], v[104:105]
	v_pk_fma_f32 v[180:181], v[84:85], v[168:169], v[142:143] neg_lo:[0,0,1] neg_hi:[0,0,1]
	v_pk_mul_f32 v[142:143], v[84:85], v[150:151]
	v_pk_mul_f32 v[104:105], v[124:125], v[156:157]
	v_pk_fma_f32 v[150:151], v[98:99], v[168:169], v[142:143]
	v_pk_mul_f32 v[142:143], v[100:101], v[154:155]
	v_pk_fma_f32 v[170:171], v[96:97], v[108:109], v[104:105] neg_lo:[0,0,1] neg_hi:[0,0,1]
	v_pk_fma_f32 v[168:169], v[90:91], v[106:107], v[142:143] neg_lo:[0,0,1] neg_hi:[0,0,1]
	v_pk_mul_f32 v[104:105], v[96:97], v[156:157]
	v_pk_mul_f32 v[142:143], v[90:91], v[154:155]
	v_pk_fma_f32 v[108:109], v[124:125], v[108:109], v[104:105]
	v_pk_fma_f32 v[106:107], v[100:101], v[106:107], v[142:143]
	v_mfma_f32_16x16x16_bf16 v[172:175], v[114:115], v[166:167], v[172:175]
	v_mul_f32_e64 v142, v88, v138
	v_mul_f32_e64 v143, v89, v139
	v_pk_mul_f32 v[138:139], v[78:79], v[138:139]
	v_mfma_f32_16x16x16_bf16 v[176:179], v[126:127], v[166:167], v[176:179]
	v_mfma_f32_16x16x16_bf16 v[146:149], v[128:129], v[166:167], v[146:149]
	v_mfma_f32_16x16x16_bf16 v[180:183], v[130:131], v[166:167], v[180:183]
	v_mfma_f32_16x16x16_bf16 v[150:153], v[132:133], v[166:167], v[150:153]
	v_mfma_f32_16x16x16_bf16 v[156:159], v[134:135], v[166:167], v[168:171]
	v_mfma_f32_16x16x16_bf16 v[104:107], v[136:137], v[166:167], v[106:109]
	ds_read2_b64 v[164:167], v163 offset0:32 offset1:36
	s_nop 0
	v_pk_fma_f32 v[168:169], v[78:79], v[172:173], v[142:143] neg_lo:[0,0,1] neg_hi:[0,0,1]
	v_pk_mul_f32 v[108:109], v[118:119], v[140:141]
	s_nop 0
	v_pk_fma_f32 v[170:171], v[80:81], v[174:175], v[108:109] neg_lo:[0,0,1] neg_hi:[0,0,1]
	v_pk_mul_f32 v[108:109], v[80:81], v[140:141]
	s_waitcnt lgkmcnt(0)
; #define LAS __attribute__((address_space(3)))
; #define S5_UPDATE(K, hre, him, xq) do { const v2u xb_ = (xq); \
;     _Pragma("unroll") for (int j = 0; j < 4; ++j) { const f32x4 cre_ = K.ar[j] * hre[j] - K.ai[j] * him[j], cim_ = K.ar[j] * him[j] + K.ai[j] * hre[j]; \
;         hre[j] = MFMA16K16(K.Bf[2 * j], xb_, cre_); him[j] = MFMA16K16(K.Bf[2 * j + 1], xb_, cim_); } } while (0)
; __device__ __forceinline__ void s5_prompt_task(const Args& a, const Ctx& C, int b, int g, v4u (&xv)[8]) {
;     ...
;     const int chunk = 16 * w + n;
;     f32x4 hre[4], him[4];
; #pragma unroll
;     for (int j = 0; j < 4; ++j) { hre[j] = (f32x4){0.f, 0.f, 0.f, 0.f}; him[j] = (f32x4){0.f, 0.f, 0.f, 0.f}; }
;     const LAS unsigned char* xsl = XS + chunk * 528 + q * 8;
;     for (int t = 0; t < 16; ++t) { const v2u xq = *(const LAS v2u*)(xsl + t * 32); S5_UPDATE(K, hre, him, xq); }
	v_mfma_f32_16x16x16_bf16 v[140:143], v[114:115], v[164:165], v[168:171]
	s_nop 2
	v_fma_f32 v170, v118, v174, v108
	v_fma_f32 v171, v119, v175, v109
	v_pk_fma_f32 v[168:169], v[88:89], v[172:173], v[138:139]
	v_pk_mul_f32 v[108:109], v[120:121], v[148:149]
	v_pk_mul_f32 v[138:139], v[94:95], v[146:147]
	v_pk_fma_f32 v[174:175], v[86:87], v[178:179], v[108:109] neg_lo:[0,0,1] neg_hi:[0,0,1]
	v_pk_fma_f32 v[172:173], v[82:83], v[176:177], v[138:139] neg_lo:[0,0,1] neg_hi:[0,0,1]
	v_pk_mul_f32 v[108:109], v[86:87], v[148:149]
	v_pk_mul_f32 v[138:139], v[82:83], v[146:147]
	v_mfma_f32_16x16x16_bf16 v[168:171], v[116:117], v[164:165], v[168:171]
	v_fma_f32 v148, v120, v178, v108
	v_fma_f32 v149, v121, v179, v109
	v_pk_fma_f32 v[146:147], v[94:95], v[176:177], v[138:139]
	v_pk_mul_f32 v[108:109], v[122:123], v[152:153]
	v_pk_mul_f32 v[138:139], v[98:99], v[150:151]
	v_pk_fma_f32 v[178:179], v[92:93], v[182:183], v[108:109] neg_lo:[0,0,1] neg_hi:[0,0,1]
	v_pk_fma_f32 v[176:177], v[84:85], v[180:181], v[138:139] neg_lo:[0,0,1] neg_hi:[0,0,1]
	v_pk_mul_f32 v[138:139], v[84:85], v[150:151]
	v_pk_mul_f32 v[108:109], v[92:93], v[152:153]
	v_mfma_f32_16x16x16_bf16 v[152:155], v[130:131], v[164:165], v[176:179]
	s_nop 2
	v_fma_f32 v176, v98, v180, v138
	v_fma_f32 v177, v99, v181, v139
	v_pk_mul_f32 v[138:139], v[100:101], v[104:105]
	v_mfma_f32_16x16x16_bf16 v[146:149], v[128:129], v[164:165], v[146:149]
	v_fma_f32 v178, v122, v182, v108
	v_fma_f32 v179, v123, v183, v109
	v_pk_mul_f32 v[108:109], v[124:125], v[106:107]
	v_pk_fma_f32 v[180:181], v[90:91], v[156:157], v[138:139] neg_lo:[0,0,1] neg_hi:[0,0,1]
	v_pk_mul_f32 v[138:139], v[96:97], v[106:107]
	v_pk_mul_f32 v[104:105], v[90:91], v[104:105]
	v_mfma_f32_16x16x16_bf16 v[172:175], v[126:127], v[164:165], v[172:175]
	v_fma_f32 v182, v96, v158, -v108
	v_fma_f32 v183, v97, v159, -v109
	v_pk_fma_f32 v[158:159], v[124:125], v[158:159], v[138:139]
	v_pk_fma_f32 v[156:157], v[100:101], v[156:157], v[104:105]
	v_pk_mul_f32 v[104:105], v[118:119], v[170:171]
	v_pk_mul_f32 v[138:139], v[88:89], v[168:169]
	v_mfma_f32_16x16x16_bf16 v[176:179], v[132:133], v[164:165], v[176:179]
	v_mfma_f32_16x16x16_bf16 v[106:109], v[134:135], v[164:165], v[180:183]
	s_nop 2
	v_fma_f32 v182, v80, v142, -v104
	v_fma_f32 v183, v81, v143, -v105
	v_pk_fma_f32 v[180:181], v[78:79], v[140:141], v[138:139] neg_lo:[0,0,1] neg_hi:[0,0,1]
	v_pk_mul_f32 v[104:105], v[80:81], v[170:171]
	v_pk_mul_f32 v[138:139], v[78:79], v[168:169]
	v_pk_fma_f32 v[142:143], v[118:119], v[142:143], v[104:105]
	v_pk_fma_f32 v[140:141], v[88:89], v[140:141], v[138:139]
	v_mfma_f32_16x16x16_bf16 v[156:159], v[136:137], v[164:165], v[156:159]
	v_mul_f32_e64 v104, v120, v148
	v_mul_f32_e64 v105, v121, v149
	v_pk_fma_f32 v[170:171], v[86:87], v[174:175], v[104:105] neg_lo:[0,0,1] neg_hi:[0,0,1]
	v_mfma_f32_16x16x16_bf16 v[138:141], v[116:117], v[166:167], v[140:143]
	v_mul_f32_e64 v104, v86, v148
	v_mul_f32_e64 v105, v87, v149
	s_nop 0
	v_pk_mul_f32 v[142:143], v[94:95], v[146:147]
	v_mfma_f32_16x16x16_bf16 v[180:183], v[114:115], v[166:167], v[180:183]
	v_fma_f32 v168, v82, v172, -v142
	v_fma_f32 v169, v83, v173, -v143
	v_pk_mul_f32 v[142:143], v[82:83], v[146:147]
	s_nop 0
	v_mfma_f32_16x16x16_bf16 v[148:151], v[126:127], v[166:167], v[168:171]
	s_nop 2
	v_fma_f32 v170, v120, v174, v104
	v_fma_f32 v171, v121, v175, v105
	v_pk_fma_f32 v[168:169], v[94:95], v[172:173], v[142:143]
	v_pk_mul_f32 v[104:105], v[122:123], v[178:179]
	v_pk_mul_f32 v[142:143], v[98:99], v[176:177]
	v_pk_fma_f32 v[174:175], v[92:93], v[154:155], v[104:105] neg_lo:[0,0,1] neg_hi:[0,0,1]
	v_pk_fma_f32 v[172:173], v[84:85], v[152:153], v[142:143] neg_lo:[0,0,1] neg_hi:[0,0,1]
	v_pk_mul_f32 v[104:105], v[92:93], v[178:179]
	v_pk_mul_f32 v[142:143], v[84:85], v[176:177]
	v_pk_fma_f32 v[154:155], v[122:123], v[154:155], v[104:105]
	v_pk_fma_f32 v[152:153], v[98:99], v[152:153], v[142:143]
	v_pk_mul_f32 v[104:105], v[124:125], v[158:159]
	v_pk_mul_f32 v[142:143], v[100:101], v[156:157]
	v_pk_fma_f32 v[178:179], v[96:97], v[108:109], v[104:105] neg_lo:[0,0,1] neg_hi:[0,0,1]
	v_pk_fma_f32 v[176:177], v[90:91], v[106:107], v[142:143] neg_lo:[0,0,1] neg_hi:[0,0,1]
	v_pk_mul_f32 v[104:105], v[96:97], v[158:159]
	v_pk_mul_f32 v[142:143], v[90:91], v[156:157]
	ds_read2_b64 v[156:159], v163 offset0:40 offset1:44
	v_mfma_f32_16x16x16_bf16 v[168:171], v[128:129], v[166:167], v[168:171]
	v_fma_f32 v108, v124, v108, v104
	v_fma_f32 v109, v125, v109, v105
	v_pk_fma_f32 v[106:107], v[100:101], v[106:107], v[142:143]
	v_pk_mul_f32 v[142:143], v[88:89], v[138:139]
	v_mfma_f32_16x16x16_bf16 v[152:155], v[132:133], v[166:167], v[152:155]
	v_fma_f32 v164, v78, v180, -v142
	v_fma_f32 v165, v79, v181, -v143
	v_pk_mul_f32 v[138:139], v[78:79], v[138:139]
	v_mfma_f32_16x16x16_bf16 v[104:107], v[136:137], v[166:167], v[106:109]
	s_nop 2
	v_mul_f32_e64 v108, v118, v140
	v_mul_f32_e64 v109, v119, v141
	v_mfma_f32_16x16x16_bf16 v[172:175], v[130:131], v[166:167], v[172:175]
	v_mfma_f32_16x16x16_bf16 v[176:179], v[134:135], v[166:167], v[176:179]
	v_fma_f32 v166, v80, v182, -v108
	v_fma_f32 v167, v81, v183, -v109
	v_pk_mul_f32 v[108:109], v[80:81], v[140:141]
	s_waitcnt lgkmcnt(0)
; #define LAS __attribute__((address_space(3)))
; #define S5_UPDATE(K, hre, him, xq) do { const v2u xb_ = (xq); \
;     _Pragma("unroll") for (int j = 0; j < 4; ++j) { const f32x4 cre_ = K.ar[j] * hre[j] - K.ai[j] * him[j], cim_ = K.ar[j] * him[j] + K.ai[j] * hre[j]; \
;         hre[j] = MFMA16K16(K.Bf[2 * j], xb_, cre_); him[j] = MFMA16K16(K.Bf[2 * j + 1], xb_, cim_); } } while (0)
; __device__ __forceinline__ void s5_prompt_task(const Args& a, const Ctx& C, int b, int g, v4u (&xv)[8]) {
;     ...
;     const int chunk = 16 * w + n;
;     f32x4 hre[4], him[4];
; #pragma unroll
;     for (int j = 0; j < 4; ++j) { hre[j] = (f32x4){0.f, 0.f, 0.f, 0.f}; him[j] = (f32x4){0.f, 0.f, 0.f, 0.f}; }
;     const LAS unsigned char* xsl = XS + chunk * 528 + q * 8;
;     for (int t = 0; t < 16; ++t) { const v2u xq = *(const LAS v2u*)(xsl + t * 32); S5_UPDATE(K, hre, him, xq); }
	v_mfma_f32_16x16x16_bf16 v[140:143], v[114:115], v[156:157], v[164:167]
	s_nop 2
	v_fma_f32 v166, v118, v182, v108
	v_fma_f32 v167, v119, v183, v109
	v_pk_fma_f32 v[164:165], v[88:89], v[180:181], v[138:139]
	v_pk_mul_f32 v[108:109], v[120:121], v[170:171]
	v_pk_mul_f32 v[138:139], v[94:95], v[168:169]
	v_pk_fma_f32 v[182:183], v[86:87], v[150:151], v[108:109] neg_lo:[0,0,1] neg_hi:[0,0,1]
	v_pk_fma_f32 v[180:181], v[82:83], v[148:149], v[138:139] neg_lo:[0,0,1] neg_hi:[0,0,1]
	v_pk_mul_f32 v[108:109], v[86:87], v[170:171]
	v_pk_mul_f32 v[138:139], v[82:83], v[168:169]
	v_mfma_f32_16x16x16_bf16 v[164:167], v[116:117], v[156:157], v[164:167]
	v_fma_f32 v150, v120, v150, v108
	v_fma_f32 v151, v121, v151, v109
	v_pk_fma_f32 v[148:149], v[94:95], v[148:149], v[138:139]
	v_pk_mul_f32 v[108:109], v[122:123], v[154:155]
	v_pk_mul_f32 v[138:139], v[98:99], v[152:153]
	v_pk_fma_f32 v[170:171], v[92:93], v[174:175], v[108:109] neg_lo:[0,0,1] neg_hi:[0,0,1]
	v_pk_fma_f32 v[168:169], v[84:85], v[172:173], v[138:139] neg_lo:[0,0,1] neg_hi:[0,0,1]
	v_pk_mul_f32 v[108:109], v[92:93], v[154:155]
	v_pk_mul_f32 v[138:139], v[84:85], v[152:153]
	v_mfma_f32_16x16x16_bf16 v[146:149], v[128:129], v[156:157], v[148:151]
	v_fma_f32 v152, v122, v174, v108
	v_fma_f32 v153, v123, v175, v109
	v_pk_mul_f32 v[108:109], v[124:125], v[106:107]
	v_pk_fma_f32 v[150:151], v[98:99], v[172:173], v[138:139]
	v_pk_mul_f32 v[138:139], v[100:101], v[104:105]
	v_pk_fma_f32 v[174:175], v[96:97], v[178:179], v[108:109] neg_lo:[0,0,1] neg_hi:[0,0,1]
	v_pk_fma_f32 v[172:173], v[90:91], v[176:177], v[138:139] neg_lo:[0,0,1] neg_hi:[0,0,1]
	v_pk_mul_f32 v[138:139], v[96:97], v[106:107]
	v_pk_mul_f32 v[104:105], v[90:91], v[104:105]
	v_mfma_f32_16x16x16_bf16 v[180:183], v[126:127], v[156:157], v[180:183]
	v_mfma_f32_16x16x16_bf16 v[106:109], v[134:135], v[156:157], v[172:175]
	s_nop 2
	v_fma_f32 v174, v124, v178, v138
	v_fma_f32 v175, v125, v179, v139
	v_pk_fma_f32 v[172:173], v[100:101], v[176:177], v[104:105]
	v_pk_mul_f32 v[104:105], v[118:119], v[166:167]
	v_pk_mul_f32 v[138:139], v[88:89], v[164:165]
	v_mfma_f32_16x16x16_bf16 v[168:171], v[130:131], v[156:157], v[168:171]
	v_mfma_f32_16x16x16_bf16 v[150:153], v[132:133], v[156:157], v[150:153]
	v_mfma_f32_16x16x16_bf16 v[154:157], v[136:137], v[156:157], v[172:175]
	s_nop 2
	v_fma_f32 v174, v80, v142, -v104
	v_fma_f32 v175, v81, v143, -v105
	v_pk_fma_f32 v[172:173], v[78:79], v[140:141], v[138:139] neg_lo:[0,0,1] neg_hi:[0,0,1]
	v_pk_mul_f32 v[104:105], v[80:81], v[166:167]
	v_pk_mul_f32 v[138:139], v[78:79], v[164:165]
	v_pk_fma_f32 v[142:143], v[118:119], v[142:143], v[104:105]
	v_pk_fma_f32 v[140:141], v[88:89], v[140:141], v[138:139]
	v_pk_mul_f32 v[104:105], v[120:121], v[148:149]
	v_mfma_f32_16x16x16_bf16 v[172:175], v[114:115], v[158:159], v[172:175]
	v_fma_f32 v166, v86, v182, -v104
	v_fma_f32 v167, v87, v183, -v105
	v_pk_mul_f32 v[104:105], v[86:87], v[148:149]
	v_mfma_f32_16x16x16_bf16 v[138:141], v[116:117], v[158:159], v[140:143]
	v_fma_f32 v148, v120, v182, v104
	v_fma_f32 v149, v121, v183, v105
	v_pk_mul_f32 v[104:105], v[122:123], v[152:153]
	v_pk_mul_f32 v[142:143], v[94:95], v[146:147]
	v_pk_fma_f32 v[178:179], v[92:93], v[170:171], v[104:105] neg_lo:[0,0,1] neg_hi:[0,0,1]
	v_pk_fma_f32 v[164:165], v[82:83], v[180:181], v[142:143] neg_lo:[0,0,1] neg_hi:[0,0,1]
	v_pk_mul_f32 v[142:143], v[82:83], v[146:147]
	v_pk_mul_f32 v[104:105], v[92:93], v[152:153]
	v_pk_fma_f32 v[146:147], v[94:95], v[180:181], v[142:143]
	v_pk_mul_f32 v[142:143], v[98:99], v[150:151]
	v_pk_fma_f32 v[152:153], v[122:123], v[170:171], v[104:105]
	v_pk_fma_f32 v[176:177], v[84:85], v[168:169], v[142:143] neg_lo:[0,0,1] neg_hi:[0,0,1]
	v_pk_mul_f32 v[142:143], v[84:85], v[150:151]
	v_pk_mul_f32 v[104:105], v[124:125], v[156:157]
	v_pk_fma_f32 v[150:151], v[98:99], v[168:169], v[142:143]
	v_pk_mul_f32 v[142:143], v[100:101], v[154:155]
	v_mfma_f32_16x16x16_bf16 v[146:149], v[128:129], v[158:159], v[146:149]
	v_fma_f32 v170, v96, v108, -v104
	v_fma_f32 v171, v97, v109, -v105
	v_pk_fma_f32 v[168:169], v[90:91], v[106:107], v[142:143] neg_lo:[0,0,1] neg_hi:[0,0,1]
	v_pk_mul_f32 v[104:105], v[96:97], v[156:157]
	v_pk_mul_f32 v[142:143], v[90:91], v[154:155]
	ds_read2_b64 v[154:157], v163 offset0:48 offset1:52
	v_mfma_f32_16x16x16_bf16 v[164:167], v[126:127], v[158:159], v[164:167]
	v_fma_f32 v108, v124, v108, v104
	v_fma_f32 v109, v125, v109, v105
	v_pk_fma_f32 v[106:107], v[100:101], v[106:107], v[142:143]
	v_pk_mul_f32 v[142:143], v[88:89], v[138:139]
	v_mfma_f32_16x16x16_bf16 v[150:153], v[132:133], v[158:159], v[150:153]
	v_mul_f32_e64 v138, v78, v138
	v_mul_f32_e64 v139, v79, v139
	v_pk_fma_f32 v[180:181], v[78:79], v[172:173], v[142:143] neg_lo:[0,0,1] neg_hi:[0,0,1]
	v_pk_fma_f32 v[172:173], v[88:89], v[172:173], v[138:139]
	v_mfma_f32_16x16x16_bf16 v[176:179], v[130:131], v[158:159], v[176:179]
	v_mul_f32_e64 v138, v94, v146
	v_mul_f32_e64 v139, v95, v147
	v_mfma_f32_16x16x16_bf16 v[104:107], v[136:137], v[158:159], v[106:109]
	s_nop 2
	v_mul_f32_e64 v108, v118, v140
	v_mul_f32_e64 v109, v119, v141
	v_mfma_f32_16x16x16_bf16 v[168:171], v[134:135], v[158:159], v[168:171]
	v_fma_f32 v182, v80, v174, -v108
	v_fma_f32 v183, v81, v175, -v109
	v_pk_mul_f32 v[108:109], v[80:81], v[140:141]
	s_waitcnt lgkmcnt(0)
; #define LAS __attribute__((address_space(3)))
; #define S5_UPDATE(K, hre, him, xq) do { const v2u xb_ = (xq); \
;     _Pragma("unroll") for (int j = 0; j < 4; ++j) { const f32x4 cre_ = K.ar[j] * hre[j] - K.ai[j] * him[j], cim_ = K.ar[j] * him[j] + K.ai[j] * hre[j]; \
;         hre[j] = MFMA16K16(K.Bf[2 * j], xb_, cre_); him[j] = MFMA16K16(K.Bf[2 * j + 1], xb_, cim_); } } while (0)
; __device__ __forceinline__ void s5_prompt_task(const Args& a, const Ctx& C, int b, int g, v4u (&xv)[8]) {
;     ...
;     const int chunk = 16 * w + n;
;     f32x4 hre[4], him[4];
; #pragma unroll
;     for (int j = 0; j < 4; ++j) { hre[j] = (f32x4){0.f, 0.f, 0.f, 0.f}; him[j] = (f32x4){0.f, 0.f, 0.f, 0.f}; }
;     const LAS unsigned char* xsl = XS + chunk * 528 + q * 8;
;     for (int t = 0; t < 16; ++t) { const v2u xq = *(const LAS v2u*)(xsl + t * 32); S5_UPDATE(K, hre, him, xq); }
	v_mfma_f32_16x16x16_bf16 v[140:143], v[114:115], v[154:155], v[180:183]
	v_fma_f32 v174, v118, v174, v108
	v_fma_f32 v175, v119, v175, v109
	v_pk_mul_f32 v[108:109], v[120:121], v[148:149]
	v_pk_fma_f32 v[180:181], v[82:83], v[164:165], v[138:139] neg_lo:[0,0,1] neg_hi:[0,0,1]
	v_pk_mul_f32 v[138:139], v[82:83], v[146:147]
	v_mfma_f32_16x16x16_bf16 v[172:175], v[116:117], v[154:155], v[172:175]
	v_fma_f32 v182, v86, v166, -v108
	v_fma_f32 v183, v87, v167, -v109
	v_pk_mul_f32 v[108:109], v[86:87], v[148:149]
	v_pk_fma_f32 v[146:147], v[94:95], v[164:165], v[138:139]
	v_pk_mul_f32 v[138:139], v[98:99], v[150:151]
	v_pk_fma_f32 v[148:149], v[120:121], v[166:167], v[108:109]
	v_pk_mul_f32 v[108:109], v[122:123], v[152:153]
	v_pk_fma_f32 v[164:165], v[84:85], v[176:177], v[138:139] neg_lo:[0,0,1] neg_hi:[0,0,1]
	v_pk_mul_f32 v[138:139], v[84:85], v[150:151]
	v_pk_fma_f32 v[166:167], v[92:93], v[178:179], v[108:109] neg_lo:[0,0,1] neg_hi:[0,0,1]
	v_pk_mul_f32 v[108:109], v[92:93], v[152:153]
	v_pk_fma_f32 v[150:151], v[98:99], v[176:177], v[138:139]
	v_pk_mul_f32 v[138:139], v[100:101], v[104:105]
	v_mfma_f32_16x16x16_bf16 v[146:149], v[128:129], v[154:155], v[146:149]
	v_fma_f32 v152, v122, v178, v108
	v_fma_f32 v153, v123, v179, v109
	v_pk_mul_f32 v[108:109], v[124:125], v[106:107]
	v_pk_fma_f32 v[176:177], v[90:91], v[168:169], v[138:139] neg_lo:[0,0,1] neg_hi:[0,0,1]
	v_pk_mul_f32 v[138:139], v[96:97], v[106:107]
	v_pk_mul_f32 v[104:105], v[90:91], v[104:105]
	v_mfma_f32_16x16x16_bf16 v[180:183], v[126:127], v[154:155], v[180:183]
	v_fma_f32 v178, v96, v170, -v108
	v_fma_f32 v179, v97, v171, -v109
	v_pk_fma_f32 v[170:171], v[124:125], v[170:171], v[138:139]
	v_pk_fma_f32 v[168:169], v[100:101], v[168:169], v[104:105]
	v_pk_mul_f32 v[104:105], v[118:119], v[174:175]
	v_pk_mul_f32 v[138:139], v[88:89], v[172:173]
	v_mfma_f32_16x16x16_bf16 v[150:153], v[132:133], v[154:155], v[150:153]
	v_mfma_f32_16x16x16_bf16 v[106:109], v[134:135], v[154:155], v[176:179]
	s_nop 2
	v_fma_f32 v178, v80, v142, -v104
	v_fma_f32 v179, v81, v143, -v105
	v_pk_fma_f32 v[176:177], v[78:79], v[140:141], v[138:139] neg_lo:[0,0,1] neg_hi:[0,0,1]
	v_pk_mul_f32 v[104:105], v[80:81], v[174:175]
	v_pk_mul_f32 v[138:139], v[78:79], v[172:173]
	v_mfma_f32_16x16x16_bf16 v[164:167], v[130:131], v[154:155], v[164:167]
	v_fma_f32 v142, v118, v142, v104
	v_fma_f32 v143, v119, v143, v105
	v_pk_fma_f32 v[140:141], v[88:89], v[140:141], v[138:139]
	v_pk_mul_f32 v[104:105], v[120:121], v[148:149]
	v_mfma_f32_16x16x16_bf16 v[168:171], v[136:137], v[154:155], v[168:171]
	v_fma_f32 v186, v86, v182, -v104
	v_fma_f32 v187, v87, v183, -v105
	v_pk_mul_f32 v[104:105], v[86:87], v[148:149]
	v_mfma_f32_16x16x16_bf16 v[138:141], v[116:117], v[156:157], v[140:143]
	v_fma_f32 v148, v120, v182, v104
	v_fma_f32 v149, v121, v183, v105
	v_pk_mul_f32 v[104:105], v[122:123], v[152:153]
	v_pk_mul_f32 v[142:143], v[94:95], v[146:147]
	v_mfma_f32_16x16x16_bf16 v[174:177], v[114:115], v[156:157], v[176:179]
	v_fma_f32 v184, v82, v180, -v142
	v_fma_f32 v185, v83, v181, -v143
	v_pk_mul_f32 v[142:143], v[82:83], v[146:147]
	s_nop 0
	v_pk_fma_f32 v[146:147], v[94:95], v[180:181], v[142:143]
	v_pk_mul_f32 v[142:143], v[98:99], v[150:151]
	v_pk_fma_f32 v[180:181], v[92:93], v[166:167], v[104:105] neg_lo:[0,0,1] neg_hi:[0,0,1]
	v_pk_fma_f32 v[178:179], v[84:85], v[164:165], v[142:143] neg_lo:[0,0,1] neg_hi:[0,0,1]
	v_pk_mul_f32 v[104:105], v[92:93], v[152:153]
	v_pk_mul_f32 v[142:143], v[84:85], v[150:151]
	v_pk_fma_f32 v[166:167], v[122:123], v[166:167], v[104:105]
	v_pk_fma_f32 v[164:165], v[98:99], v[164:165], v[142:143]
	v_pk_mul_f32 v[104:105], v[124:125], v[170:171]
	v_pk_mul_f32 v[142:143], v[100:101], v[168:169]
	v_mfma_f32_16x16x16_bf16 v[152:155], v[130:131], v[156:157], v[178:181]
	s_nop 2
	v_fma_f32 v180, v96, v108, -v104
	v_fma_f32 v181, v97, v109, -v105
	v_pk_fma_f32 v[178:179], v[90:91], v[106:107], v[142:143] neg_lo:[0,0,1] neg_hi:[0,0,1]
	v_pk_mul_f32 v[104:105], v[96:97], v[170:171]
	v_pk_mul_f32 v[142:143], v[90:91], v[168:169]
	v_pk_fma_f32 v[108:109], v[124:125], v[108:109], v[104:105]
	v_pk_fma_f32 v[106:107], v[100:101], v[106:107], v[142:143]
	v_mfma_f32_16x16x16_bf16 v[184:187], v[126:127], v[156:157], v[184:187]
	v_mul_f32_e64 v142, v88, v138
	v_mul_f32_e64 v143, v89, v139
	v_pk_mul_f32 v[138:139], v[78:79], v[138:139]
	v_mfma_f32_16x16x16_bf16 v[146:149], v[128:129], v[156:157], v[146:149]
	v_mfma_f32_16x16x16_bf16 v[164:167], v[132:133], v[156:157], v[164:167]
	v_mfma_f32_16x16x16_bf16 v[170:173], v[134:135], v[156:157], v[178:181]
	v_mfma_f32_16x16x16_bf16 v[104:107], v[136:137], v[156:157], v[106:109]
	ds_read2_b64 v[156:159], v163 offset0:56 offset1:60
	s_nop 0
	v_pk_fma_f32 v[178:179], v[78:79], v[174:175], v[142:143] neg_lo:[0,0,1] neg_hi:[0,0,1]
	v_pk_fma_f32 v[174:175], v[88:89], v[174:175], v[138:139]
	v_pk_mul_f32 v[108:109], v[118:119], v[140:141]
	v_pk_mul_f32 v[138:139], v[94:95], v[146:147]
	v_pk_fma_f32 v[180:181], v[80:81], v[176:177], v[108:109] neg_lo:[0,0,1] neg_hi:[0,0,1]
	v_pk_mul_f32 v[108:109], v[80:81], v[140:141]
	s_nop 0
	v_pk_fma_f32 v[176:177], v[118:119], v[176:177], v[108:109]
	v_pk_mul_f32 v[108:109], v[120:121], v[148:149]
	s_waitcnt lgkmcnt(0)
; #define LAS __attribute__((address_space(3)))
; #define S5_UPDATE(K, hre, him, xq) do { const v2u xb_ = (xq); \
;     _Pragma("unroll") for (int j = 0; j < 4; ++j) { const f32x4 cre_ = K.ar[j] * hre[j] - K.ai[j] * him[j], cim_ = K.ar[j] * him[j] + K.ai[j] * hre[j]; \
;         hre[j] = MFMA16K16(K.Bf[2 * j], xb_, cre_); him[j] = MFMA16K16(K.Bf[2 * j + 1], xb_, cim_); } } while (0)
; __device__ __forceinline__ void s5_prompt_task(const Args& a, const Ctx& C, int b, int g, v4u (&xv)[8]) {
;     ...
;     for (int t = 0; t < 16; ++t) { const v2u xq = *(const LAS v2u*)(xsl + t * 32); S5_UPDATE(K, hre, him, xq); }
; #pragma unroll
;     for (int j = 0; j < 4; ++j) { LAS float* d = SH + chunk * 132 + 2 * (16 * j + 4 * q);
;         *(LAS f32x4*)d = (f32x4){hre[j][0], him[j][0], hre[j][1], him[j][1]}; *(LAS f32x4*)(d + 4) = (f32x4){hre[j][2], him[j][2], hre[j][3], him[j][3]}; }
;     v2u zq[4];
; #pragma unroll
;     for (int t = 0; t < 4; ++t) zq[t] = __builtin_nontemporal_load((const v2u*)(ZBg + (size_t)(16 * chunk + t) * 16 + 4 * q));
	v_mfma_f32_16x16x16_bf16 v[140:143], v[114:115], v[156:157], v[178:181]
	s_nop 2
	v_fma_f32 v180, v86, v186, -v108
	v_fma_f32 v181, v87, v187, -v109
	v_pk_fma_f32 v[178:179], v[82:83], v[184:185], v[138:139] neg_lo:[0,0,1] neg_hi:[0,0,1]
	v_pk_mul_f32 v[138:139], v[82:83], v[146:147]
	v_mfma_f32_16x16x16_bf16 v[174:177], v[116:117], v[156:157], v[174:177]
	v_mul_f32_e64 v108, v86, v148
	v_mul_f32_e64 v109, v87, v149
	v_mfma_f32_16x16x16_bf16 v[148:151], v[126:127], v[156:157], v[178:181]
	s_nop 2
	v_fma_f32 v178, v94, v184, v138
	v_fma_f32 v179, v95, v185, v139
	v_pk_mul_f32 v[138:139], v[98:99], v[164:165]
	v_pk_fma_f32 v[180:181], v[120:121], v[186:187], v[108:109]
	v_pk_mul_f32 v[108:109], v[122:123], v[166:167]
	v_pk_fma_f32 v[182:183], v[84:85], v[152:153], v[138:139] neg_lo:[0,0,1] neg_hi:[0,0,1]
	v_pk_mul_f32 v[138:139], v[84:85], v[164:165]
	v_mfma_f32_16x16x16_bf16 v[178:181], v[128:129], v[156:157], v[178:181]
	v_fma_f32 v184, v92, v154, -v108
	v_fma_f32 v185, v93, v155, -v109
	v_pk_mul_f32 v[108:109], v[92:93], v[166:167]
	v_pk_fma_f32 v[152:153], v[98:99], v[152:153], v[138:139]
	v_pk_mul_f32 v[138:139], v[100:101], v[104:105]
	v_mfma_f32_16x16x16_bf16 v[166:169], v[130:131], v[156:157], v[182:185]
	v_fma_f32 v154, v122, v154, v108
	v_fma_f32 v155, v123, v155, v109
	v_pk_mul_f32 v[108:109], v[124:125], v[106:107]
	v_pk_mul_f32 v[104:105], v[90:91], v[104:105]
	v_pk_fma_f32 v[182:183], v[90:91], v[170:171], v[138:139] neg_lo:[0,0,1] neg_hi:[0,0,1]
	v_pk_mul_f32 v[138:139], v[96:97], v[106:107]
	v_mfma_f32_16x16x16_bf16 v[152:155], v[132:133], v[156:157], v[152:155]
	v_fma_f32 v184, v96, v172, -v108
	v_fma_f32 v185, v97, v173, -v109
	v_pk_fma_f32 v[172:173], v[124:125], v[172:173], v[138:139]
	v_pk_mul_f32 v[138:139], v[88:89], v[174:175]
	v_mfma_f32_16x16x16_bf16 v[106:109], v[134:135], v[156:157], v[182:185]
	v_fma_f32 v170, v100, v170, v104
	v_fma_f32 v171, v101, v171, v105
	v_pk_mul_f32 v[104:105], v[118:119], v[176:177]
	v_pk_fma_f32 v[182:183], v[78:79], v[140:141], v[138:139] neg_lo:[0,0,1] neg_hi:[0,0,1]
	v_pk_mul_f32 v[78:79], v[78:79], v[174:175]
	v_mfma_f32_16x16x16_bf16 v[170:173], v[136:137], v[156:157], v[170:173]
	v_fma_f32 v184, v80, v142, -v104
	v_fma_f32 v185, v81, v143, -v105
	v_pk_fma_f32 v[78:79], v[88:89], v[140:141], v[78:79]
	v_pk_mul_f32 v[88:89], v[120:121], v[180:181]
	v_pk_mul_f32 v[104:105], v[94:95], v[178:179]
	v_pk_fma_f32 v[140:141], v[86:87], v[150:151], v[88:89] neg_lo:[0,0,1] neg_hi:[0,0,1]
	v_pk_fma_f32 v[138:139], v[82:83], v[148:149], v[104:105] neg_lo:[0,0,1] neg_hi:[0,0,1]
	v_pk_mul_f32 v[82:83], v[82:83], v[178:179]
	v_pk_mul_f32 v[80:81], v[80:81], v[176:177]
	v_pk_mul_f32 v[104:105], v[86:87], v[180:181]
	v_mfma_f32_16x16x16_bf16 v[86:89], v[126:127], v[158:159], v[138:141]
	v_fma_f32 v80, v118, v142, v80
	v_fma_f32 v81, v119, v143, v81
	s_nop 0
	v_pk_fma_f32 v[138:139], v[94:95], v[148:149], v[82:83]
	v_pk_mul_f32 v[82:83], v[122:123], v[154:155]
	v_pk_fma_f32 v[140:141], v[120:121], v[150:151], v[104:105]
	v_pk_mul_f32 v[94:95], v[98:99], v[152:153]
	v_pk_fma_f32 v[148:149], v[92:93], v[168:169], v[82:83] neg_lo:[0,0,1] neg_hi:[0,0,1]
	v_pk_mul_f32 v[82:83], v[92:93], v[154:155]
	v_pk_mul_f32 v[104:105], v[84:85], v[152:153]
	v_mfma_f32_16x16x16_bf16 v[182:185], v[114:115], v[158:159], v[182:185]
	v_fma_f32 v146, v84, v166, -v94
	v_fma_f32 v147, v85, v167, -v95
	v_pk_fma_f32 v[84:85], v[122:123], v[168:169], v[82:83]
	v_pk_fma_f32 v[82:83], v[98:99], v[166:167], v[104:105]
	v_mfma_f32_16x16x16_bf16 v[78:81], v[116:117], v[158:159], v[78:81]
	v_mul_f32_e64 v104, v100, v170
	v_mul_f32_e64 v105, v101, v171
	v_pk_mul_f32 v[98:99], v[124:125], v[172:173]
	v_mov_b32_e32 v102, v183
	v_mfma_f32_16x16x16_bf16 v[138:141], v[128:129], v[158:159], v[138:141]
	v_lshlrev_b32_e32 v152, 3, v162
	s_nop 1
	v_mov_b32_e32 v103, v79
	v_mov_b32_e32 v79, v80
	v_mfma_f32_16x16x16_bf16 v[92:95], v[130:131], v[158:159], v[146:149]
	v_mov_b32_e32 v80, v185
	v_mov_b32_e32 v153, v111
	s_nop 0
	v_pk_fma_f32 v[146:147], v[90:91], v[106:107], v[104:105] neg_lo:[0,0,1] neg_hi:[0,0,1]
	v_pk_mul_f32 v[104:105], v[96:97], v[172:173]
	v_pk_mul_f32 v[90:91], v[90:91], v[170:171]
	v_mfma_f32_16x16x16_bf16 v[82:85], v[132:133], v[158:159], v[82:85]
	v_fma_f32 v148, v96, v108, -v98
	v_fma_f32 v149, v97, v109, -v99
	v_pk_fma_f32 v[108:109], v[124:125], v[108:109], v[104:105]
	v_pk_fma_f32 v[106:107], v[100:101], v[106:107], v[90:91]
	v_mfma_f32_16x16x16_bf16 v[96:99], v[134:135], v[158:159], v[146:149]
	v_mov_b32_e32 v101, v78
	v_mov_b32_e32 v78, v184
	ds_write_b128 v3, v[78:81] offset:16
	v_mfma_f32_16x16x16_bf16 v[104:107], v[136:137], v[158:159], v[106:109]
	v_mov_b32_e32 v78, v86
	v_mov_b32_e32 v79, v138
	v_mov_b32_e32 v80, v87
	v_mov_b32_e32 v81, v139
	ds_write_b128 v3, v[78:81] offset:128
	v_mov_b32_e32 v78, v92
	v_mov_b32_e32 v79, v82
	v_mov_b32_e32 v80, v93
	v_mov_b32_e32 v81, v83
	ds_write_b128 v3, v[78:81] offset:256
	v_mov_b32_e32 v78, v96
	v_mov_b32_e32 v79, v104
	v_mov_b32_e32 v80, v97
	v_mov_b32_e32 v81, v105
	v_mov_b32_e32 v138, v88
	v_mov_b32_e32 v139, v140
	v_mov_b32_e32 v140, v89
	v_mov_b32_e32 v82, v94
	v_mov_b32_e32 v83, v84
	v_mov_b32_e32 v84, v95
	ds_write_b128 v3, v[78:81] offset:384
	v_lshl_add_u64 v[78:79], s[4:5], 0, v[110:111]
	s_mov_b64 s[4:5], 0xd400000
	v_mov_b32_e32 v110, v7
	v_mov_b32_e32 v100, v182
	ds_write_b128 v3, v[138:141] offset:144
	ds_write_b128 v3, v[82:85] offset:272
	v_mov_b32_e32 v104, v98
	v_mov_b32_e32 v105, v106
	v_mov_b32_e32 v106, v99
	v_lshl_add_u64 v[138:139], v[78:79], 0, s[4:5]
	v_lshlrev_b64 v[78:79], 5, v[110:111]
	v_or_b32_e32 v80, 1, v7
	v_mov_b32_e32 v81, v111
	v_or_b32_e32 v82, 2, v7
	v_mov_b32_e32 v83, v111
	v_or_b32_e32 v84, 3, v7
	v_mov_b32_e32 v85, v111
	ds_write_b128 v3, v[100:103]
	ds_write_b128 v3, v[104:107] offset:400
	v_lshl_add_u64 v[78:79], v[138:139], 0, v[78:79]
	v_lshlrev_b64 v[80:81], 5, v[80:81]
	v_lshlrev_b64 v[82:83], 5, v[82:83]
	v_lshlrev_b64 v[84:85], 5, v[84:85]
	v_lshl_add_u64 v[80:81], v[138:139], 0, v[80:81]
	v_lshl_add_u64 v[82:83], v[138:139], 0, v[82:83]
	v_lshl_add_u64 v[84:85], v[138:139], 0, v[84:85]
	global_load_dwordx2 v[226:227], v[78:79], off nt
	global_load_dwordx2 v[228:229], v[80:81], off nt
	global_load_dwordx2 v[230:231], v[82:83], off nt
	global_load_dwordx2 v[232:233], v[84:85], off nt
	v_lshl_add_u64 v[78:79], s[6:7], 0, v[152:153]
	v_add_co_u32_e32 v80, vcc, s2, v78
	s_waitcnt lgkmcnt(0)
; #define LAS __attribute__((address_space(3)))
; #define LDS_WAIT() asm volatile("s_waitcnt lgkmcnt(0)" ::: "memory")
; __device__ __forceinline__ void s5_prompt_task(const Args& a, const Ctx& C, int b, int g, v4u (&xv)[8]) {
;     ...
;     LDS_WAIT();
;     { const float* A16 = (const float*)(a.ws + WS_S5C + S5C_A16) + (size_t)g * 128; const float* A256 = (const float*)(a.ws + WS_S5C + S5C_A256) + (size_t)g * 128;
;       const float a16r = A16[2 * lane], a16i = A16[2 * lane + 1], a256r = A256[2 * lane], a256i = A256[2 * lane + 1];
;       v2f sv[16];
; #pragma unroll
;       for (int i = 0; i < 16; ++i) sv[i] = *(const LAS v2f*)(SH + (16 * w + i) * 132 + 2 * lane);
;       float tr = 0.f, ti = 0.f;
; #pragma unroll
;       for (int i = 0; i < 16; ++i) { const float nr = a16r * tr - a16i * ti + sv[i][0], ni = a16r * ti + a16i * tr + sv[i][1]; tr = nr; ti = ni; }
;       TW[w * 128 + 2 * lane] = tr; TW[w * 128 + 2 * lane + 1] = ti;
;       __syncthreads();
	s_mov_b32 s2, 0x2310000
	s_nop 0
	v_addc_co_u32_e32 v81, vcc, 0, v79, vcc
	global_load_dwordx2 v[148:149], v[80:81], off
	v_add_co_u32_e32 v78, vcc, s2, v78
	v_add_u32_e32 v7, s8, v152
	s_nop 0
	v_addc_co_u32_e32 v79, vcc, 0, v79, vcc
	global_load_dwordx2 v[150:151], v[78:79], off
	s_mul_i32 s4, s82, 0x2100
	v_add_u32_e32 v7, s4, v7
	v_add_u32_e32 v11, 0x800, v7
	ds_read2_b64 v[106:109], v7 offset1:66
	ds_read2_b64 v[102:105], v7 offset0:132 offset1:198
	ds_read2_b64 v[98:101], v11 offset0:8 offset1:74
	ds_read2_b64 v[94:97], v11 offset0:140 offset1:206
	v_add_u32_e32 v11, 0x1000, v7
	ds_read2_b64 v[90:93], v11 offset0:16 offset1:82
	ds_read2_b64 v[86:89], v11 offset0:148 offset1:214
	v_add_u32_e32 v11, 0x1800, v7
	ds_read2_b64 v[82:85], v11 offset0:24 offset1:90
	ds_read2_b64 v[78:81], v11 offset0:156 offset1:222
	s_lshl_b32 s4, s82, 9
	s_add_i32 s4, s4, 0
	s_mov_b32 s2, 0
	s_cmp_lt_u32 s84, 64
	s_waitcnt vmcnt(1)
	v_mul_f32_e32 v11, 0, v148
	v_mul_f32_e32 v155, 0, v149
	v_sub_f32_e32 v154, v11, v155
	v_fmac_f32_e32 v155, 0, v148
	s_waitcnt lgkmcnt(7)
	v_pk_add_f32 v[154:155], v[154:155], v[106:107]
	v_add_u32_e32 v11, s4, v152
	v_pk_mul_f32 v[156:157], v[148:149], v[154:155] op_sel:[1,1] op_sel_hi:[0,1]
	v_pk_fma_f32 v[158:159], v[148:149], v[154:155], v[156:157] op_sel_hi:[1,0,1]
	v_pk_fma_f32 v[156:157], v[148:149], v[154:155], v[156:157] op_sel_hi:[1,0,1] neg_lo:[0,0,1] neg_hi:[0,0,1]
	v_add_u32_e32 v11, 0x21000, v11
	v_mov_b32_e32 v157, v159
	v_pk_add_f32 v[156:157], v[108:109], v[156:157]
	v_mov_b32_e32 v152, v111
	v_pk_mul_f32 v[158:159], v[148:149], v[156:157] op_sel:[1,1] op_sel_hi:[0,1]
	v_pk_fma_f32 v[164:165], v[148:149], v[156:157], v[158:159] op_sel_hi:[1,0,1]
	v_pk_fma_f32 v[158:159], v[148:149], v[156:157], v[158:159] op_sel_hi:[1,0,1] neg_lo:[0,0,1] neg_hi:[0,0,1]
	s_nop 0
	v_mov_b32_e32 v159, v165
	s_waitcnt lgkmcnt(6)
	v_pk_add_f32 v[158:159], v[102:103], v[158:159]
	s_nop 0
	v_pk_mul_f32 v[164:165], v[148:149], v[158:159] op_sel:[1,1] op_sel_hi:[0,1]
	v_pk_fma_f32 v[166:167], v[148:149], v[158:159], v[164:165] op_sel_hi:[1,0,1]
	v_pk_fma_f32 v[164:165], v[148:149], v[158:159], v[164:165] op_sel_hi:[1,0,1] neg_lo:[0,0,1] neg_hi:[0,0,1]
	s_nop 0
	v_mov_b32_e32 v165, v167
	v_pk_add_f32 v[164:165], v[104:105], v[164:165]
	s_nop 0
	v_pk_mul_f32 v[166:167], v[148:149], v[164:165] op_sel:[1,1] op_sel_hi:[0,1]
	v_pk_fma_f32 v[168:169], v[148:149], v[164:165], v[166:167] op_sel_hi:[1,0,1]
	v_pk_fma_f32 v[166:167], v[148:149], v[164:165], v[166:167] op_sel_hi:[1,0,1] neg_lo:[0,0,1] neg_hi:[0,0,1]
	s_nop 0
	v_mov_b32_e32 v167, v169
	s_waitcnt lgkmcnt(5)
	v_pk_add_f32 v[166:167], v[98:99], v[166:167]
	s_nop 0
	v_pk_mul_f32 v[168:169], v[148:149], v[166:167] op_sel:[1,1] op_sel_hi:[0,1]
	v_pk_fma_f32 v[170:171], v[148:149], v[166:167], v[168:169] op_sel_hi:[1,0,1]
	v_pk_fma_f32 v[168:169], v[148:149], v[166:167], v[168:169] op_sel_hi:[1,0,1] neg_lo:[0,0,1] neg_hi:[0,0,1]
	s_nop 0
	v_mov_b32_e32 v169, v171
	v_pk_add_f32 v[168:169], v[100:101], v[168:169]
	s_nop 0
	v_pk_mul_f32 v[170:171], v[148:149], v[168:169] op_sel:[1,1] op_sel_hi:[0,1]
	v_pk_fma_f32 v[172:173], v[148:149], v[168:169], v[170:171] op_sel_hi:[1,0,1]
	v_pk_fma_f32 v[170:171], v[148:149], v[168:169], v[170:171] op_sel_hi:[1,0,1] neg_lo:[0,0,1] neg_hi:[0,0,1]
	s_nop 0
	v_mov_b32_e32 v171, v173
	s_waitcnt lgkmcnt(4)
	v_pk_add_f32 v[170:171], v[94:95], v[170:171]
	s_nop 0
	v_pk_mul_f32 v[172:173], v[148:149], v[170:171] op_sel:[1,1] op_sel_hi:[0,1]
	v_pk_fma_f32 v[174:175], v[148:149], v[170:171], v[172:173] op_sel_hi:[1,0,1]
	v_pk_fma_f32 v[172:173], v[148:149], v[170:171], v[172:173] op_sel_hi:[1,0,1] neg_lo:[0,0,1] neg_hi:[0,0,1]
	s_nop 0
	v_mov_b32_e32 v173, v175
	v_pk_add_f32 v[172:173], v[96:97], v[172:173]
	s_nop 0
	v_pk_mul_f32 v[174:175], v[148:149], v[172:173] op_sel:[1,1] op_sel_hi:[0,1]
	v_pk_fma_f32 v[176:177], v[148:149], v[172:173], v[174:175] op_sel_hi:[1,0,1]
	v_pk_fma_f32 v[174:175], v[148:149], v[172:173], v[174:175] op_sel_hi:[1,0,1] neg_lo:[0,0,1] neg_hi:[0,0,1]
	s_nop 0
	v_mov_b32_e32 v175, v177
	s_waitcnt lgkmcnt(3)
	v_pk_add_f32 v[174:175], v[90:91], v[174:175]
	s_nop 0
	v_pk_mul_f32 v[176:177], v[148:149], v[174:175] op_sel:[1,1] op_sel_hi:[0,1]
	v_pk_fma_f32 v[178:179], v[148:149], v[174:175], v[176:177] op_sel_hi:[1,0,1]
	v_pk_fma_f32 v[176:177], v[148:149], v[174:175], v[176:177] op_sel_hi:[1,0,1] neg_lo:[0,0,1] neg_hi:[0,0,1]
	s_nop 0
	v_mov_b32_e32 v177, v179
	v_pk_add_f32 v[176:177], v[92:93], v[176:177]
	s_nop 0
	v_pk_mul_f32 v[178:179], v[148:149], v[176:177] op_sel:[1,1] op_sel_hi:[0,1]
	v_pk_fma_f32 v[180:181], v[148:149], v[176:177], v[178:179] op_sel_hi:[1,0,1]
	v_pk_fma_f32 v[178:179], v[148:149], v[176:177], v[178:179] op_sel_hi:[1,0,1] neg_lo:[0,0,1] neg_hi:[0,0,1]
	s_nop 0
	v_mov_b32_e32 v179, v181
	s_waitcnt lgkmcnt(2)
	v_pk_add_f32 v[178:179], v[86:87], v[178:179]
	s_nop 0
	v_pk_mul_f32 v[180:181], v[148:149], v[178:179] op_sel:[1,1] op_sel_hi:[0,1]
	v_pk_fma_f32 v[182:183], v[148:149], v[178:179], v[180:181] op_sel_hi:[1,0,1]
	v_pk_fma_f32 v[180:181], v[148:149], v[178:179], v[180:181] op_sel_hi:[1,0,1] neg_lo:[0,0,1] neg_hi:[0,0,1]
	s_nop 0
	v_mov_b32_e32 v181, v183
	v_pk_add_f32 v[182:183], v[88:89], v[180:181]
	s_nop 0
	v_pk_mul_f32 v[180:181], v[148:149], v[182:183] op_sel:[1,1] op_sel_hi:[0,1]
	v_pk_fma_f32 v[184:185], v[148:149], v[182:183], v[180:181] op_sel_hi:[1,0,1]
	v_pk_fma_f32 v[180:181], v[148:149], v[182:183], v[180:181] op_sel_hi:[1,0,1] neg_lo:[0,0,1] neg_hi:[0,0,1]
	s_nop 0
	v_mov_b32_e32 v181, v185
	s_waitcnt lgkmcnt(1)
	v_pk_add_f32 v[184:185], v[82:83], v[180:181]
	s_nop 0
	v_pk_mul_f32 v[180:181], v[148:149], v[184:185] op_sel:[1,1] op_sel_hi:[0,1]
	v_pk_fma_f32 v[186:187], v[148:149], v[184:185], v[180:181] op_sel_hi:[1,0,1]
	v_pk_fma_f32 v[180:181], v[148:149], v[184:185], v[180:181] op_sel_hi:[1,0,1] neg_lo:[0,0,1] neg_hi:[0,0,1]
	s_nop 0
	v_mov_b32_e32 v181, v187
	v_pk_add_f32 v[186:187], v[84:85], v[180:181]
	s_nop 0
	v_pk_mul_f32 v[180:181], v[148:149], v[186:187] op_sel:[1,1] op_sel_hi:[0,1]
	v_pk_fma_f32 v[188:189], v[148:149], v[186:187], v[180:181] op_sel_hi:[1,0,1]
	v_pk_fma_f32 v[180:181], v[148:149], v[186:187], v[180:181] op_sel_hi:[1,0,1] neg_lo:[0,0,1] neg_hi:[0,0,1]
	s_nop 0
	v_mov_b32_e32 v181, v189
	s_waitcnt lgkmcnt(0)
	v_pk_add_f32 v[188:189], v[78:79], v[180:181]
	s_nop 0
	v_pk_mul_f32 v[180:181], v[148:149], v[188:189] op_sel:[1,1] op_sel_hi:[0,1]
	v_pk_fma_f32 v[198:199], v[148:149], v[188:189], v[180:181] op_sel_hi:[1,0,1]
	v_pk_fma_f32 v[180:181], v[148:149], v[188:189], v[180:181] op_sel_hi:[1,0,1] neg_lo:[0,0,1] neg_hi:[0,0,1]
	s_nop 0
	v_mov_b32_e32 v181, v199
	v_pk_add_f32 v[180:181], v[80:81], v[180:181]
	ds_write_b64 v11, v[180:181]
	s_waitcnt lgkmcnt(0)
	s_barrier
; __device__ __forceinline__ void s5_prompt_task(const Args& a, const Ctx& C, int b, int g, v4u (&xv)[8]) {
;     ...
;       float hr = 0.f, hi = 0.f;
;       for (int v = 0; v < w; ++v) { const float sr = TW[v * 128 + 2 * lane], si = TW[v * 128 + 2 * lane + 1];
;           const float nr = a256r * hr - a256i * hi + sr, ni = a256r * hi + a256i * hr + si; hr = nr; hi = ni; }
	s_cbranch_scc1 .LBB0_985
	s_add_i32 s4, s82, -1
	s_cmp_lt_u32 s4, 7
	v_mov_b32_e32 v160, v111
	v_mov_b32_e32 v152, v111
	s_cbranch_scc1 .LBB0_977
	v_lshl_add_u32 v11, v162, 3, 0
	s_and_b32 s2, s82, 0x3fffff8
	s_waitcnt vmcnt(0)
	v_pk_mov_b32 v[154:155], v[150:151], v[150:151] op_sel:[1,0]
	s_mov_b32 s4, 0
	v_add_u32_e32 v11, 0x21000, v11
	v_mov_b32_e32 v152, 0
	v_mov_b32_e32 v160, 0

; #define LAS __attribute__((address_space(3)))
; #define MFMA16(A, B, Cc) __builtin_amdgcn_mfma_f32_16x16x32_bf16((A), (B), (Cc), 0, 0, 0)
; #define MFMA16K16(A, B, Cc) __builtin_amdgcn_mfma_f32_16x16x16bf16_1k(__builtin_bit_cast(bf16x4, (A)), __builtin_bit_cast(bf16x4, (B)), (Cc), 0, 0, 0)
; __device__ __forceinline__ unsigned pk2(float lo, float hi) { return pg8::cvt_pk_bf16(lo, hi); }
; __device__ __forceinline__ float bf_lo(unsigned w) { return __uint_as_float(w << 16); }
; __device__ __forceinline__ unsigned pk4f8(float a, float b, float c, float d) { int p = __builtin_amdgcn_cvt_pk_fp8_f32(sat8(a), sat8(b), 0, false); p = __builtin_amdgcn_cvt_pk_fp8_f32(sat8(c), sat8(d), p, true); return (unsigned)p; }
; __device__ __forceinline__ float bf_hi(unsigned w) { return __uint_as_float(w & 0xffff0000u); }
; __device__ __forceinline__ unsigned s5_output(const S5C& K, const f32x4 (&hre)[4], const f32x4 (&him)[4], v2u xq, v2u zq) {
;     f32x4 y = (f32x4){0.f, 0.f, 0.f, 0.f};
; #pragma unroll
;     for (int j = 0; j < 4; ++j) y = MFMA16(K.Cf[j], pack8(hre[j], him[j]), y);
;     const f32x4 xf = (f32x4){bf_lo(xq.x), bf_hi(xq.x), bf_lo(xq.y), bf_hi(xq.y)};
;     y = y + K.dsk * xf;
;     const v2u yb = (v2u){pk2(y[0], y[1]), pk2(y[2], y[3])};
;     const f32x4 gv = MFMA16K16(K.Wv, yb, K.bv), gg = MFMA16K16(K.Wg, yb, K.bg);
;     const f32x4 zf = (f32x4){bf_lo(zq.x), bf_hi(zq.x), bf_lo(zq.y), bf_hi(zq.y)};
;     f32x4 o;
; #pragma unroll
;     for (int r = 0; r < 4; ++r) o[r] = gv[r] * __builtin_amdgcn_rcpf(1.0f + __expf(-gg[r])) * zf[r];
;     return pk4f8(o[0], o[1], o[2], o[3]);
; __device__ __forceinline__ void s5_prompt_task(const Args& a, const Ctx& C, int b, int g, v4u (&xv)[8]) {
;     ...
; #pragma unroll 1
;     for (int t0 = 0; t0 < 16; t0 += 4) {
; #pragma unroll
;         for (int u = 0; u < 4; ++u) { const int t = t0 + u, tok = 16 * chunk + t;
;             const v2u xq = *(const LAS v2u*)(xsl + t * 32);
;             S5_UPDATE(K, hre, him, xq);
;             *(unsigned*)((unsigned char*)Y + (row0 + tok) * DM + DA + g * 16 + 4 * q) = s5_output(K, hre, him, xq, zq[u]);
;             const size_t tn = row0 + ((t + 4 < 16) ? tok + 4 : tok);
;             zq[u] = __builtin_nontemporal_load((const v2u*)(ZBg + (size_t)(tn - row0) * 16 + 4 * q)); } }
.LBB0_988:
	ds_read2_b64 v[78:81], v163 offset1:4
	v_mov_b32_e32 v119, v5
	v_mov_b32_e32 v3, v4
	v_pk_mul_f32 v[150:151], v[88:89], v[46:47]
	v_mov_b32_e32 v121, v9
	v_mov_b32_e32 v123, v13
	v_pk_mul_f32 v[142:143], v[118:119], v[48:49]
	v_pk_mul_f32 v[148:149], v[88:89], v[62:63]
	v_mov_b32_e32 v7, v8
	v_pk_mul_f32 v[154:155], v[92:93], v[54:55]
	v_mov_b32_e32 v11, v12
	v_pk_mul_f32 v[158:159], v[96:97], v[38:39]
	v_mov_b32_e32 v125, v17
	v_add_co_u32_e32 v112, vcc, s2, v106
	v_pk_mul_f32 v[140:141], v[118:119], v[64:65]
	v_pk_fma_f32 v[62:63], v[86:87], v[62:63], v[150:151]
	v_pk_mul_f32 v[146:147], v[120:121], v[56:57]
	v_pk_mul_f32 v[150:151], v[122:123], v[40:41]
	v_pk_fma_f32 v[64:65], v[2:3], v[64:65], v[142:143]
	v_pk_mul_f32 v[152:153], v[92:93], v[66:67]
	v_pk_mul_f32 v[156:157], v[96:97], v[70:71]
	v_mov_b32_e32 v15, v16
	v_pk_mul_f32 v[164:165], v[100:101], v[58:59]
	v_add_u32_e32 v108, s0, v110
	v_addc_co_u32_e32 v113, vcc, -1, v107, vcc
	s_cmp_lt_u32 s0, 12
	v_pk_fma_f32 v[46:47], v[86:87], v[46:47], v[148:149] neg_lo:[0,0,1] neg_hi:[0,0,1]
	v_pk_mul_f32 v[144:145], v[120:121], v[68:69]
	v_pk_fma_f32 v[66:67], v[90:91], v[66:67], v[154:155]
	v_pk_mul_f32 v[148:149], v[122:123], v[72:73]
	v_pk_fma_f32 v[70:71], v[94:95], v[70:71], v[158:159]
	v_pk_mul_f32 v[154:155], v[124:125], v[60:61]
	v_pk_fma_f32 v[48:49], v[2:3], v[48:49], v[140:141] neg_lo:[0,0,1] neg_hi:[0,0,1]
	s_waitcnt lgkmcnt(0)
	v_mfma_f32_16x16x16_bf16 v[62:65], v[116:117], v[78:79], v[62:65]
	v_fma_f32 v68, v6, v68, v146
	v_fma_f32 v69, v7, v69, v147
	v_pk_fma_f32 v[72:73], v[10:11], v[72:73], v[150:151]
	v_pk_mul_f32 v[160:161], v[100:101], v[74:75]
	v_pk_fma_f32 v[54:55], v[90:91], v[54:55], v[152:153] neg_lo:[0,0,1] neg_hi:[0,0,1]
	v_pk_fma_f32 v[38:39], v[94:95], v[38:39], v[156:157] neg_lo:[0,0,1] neg_hi:[0,0,1]
	v_pk_mul_f32 v[152:153], v[124:125], v[76:77]
	v_pk_fma_f32 v[74:75], v[98:99], v[74:75], v[164:165]
	v_mfma_f32_16x16x16_bf16 v[46:49], v[114:115], v[78:79], v[46:49]
	v_add_u32_e32 v140, 4, v108
	s_cselect_b64 vcc, -1, 0
	v_pk_fma_f32 v[40:41], v[10:11], v[40:41], v[148:149] neg_lo:[0,0,1] neg_hi:[0,0,1]
	v_mfma_f32_16x16x16_bf16 v[66:69], v[128:129], v[78:79], v[66:69]
	v_fma_f32 v76, v14, v76, v154
	v_fma_f32 v77, v15, v77, v155
	v_pk_fma_f32 v[58:59], v[98:99], v[58:59], v[160:161] neg_lo:[0,0,1] neg_hi:[0,0,1]
	v_add_u32_e32 v142, 1, v108
	v_mfma_f32_16x16x16_bf16 v[70:73], v[132:133], v[78:79], v[70:73]
	v_add_u32_e32 v143, 5, v108
	v_pk_fma_f32 v[56:57], v[6:7], v[56:57], v[144:145] neg_lo:[0,0,1] neg_hi:[0,0,1]
	v_add_u32_e32 v144, 2, v108
	v_add_u32_e32 v145, 6, v108
	v_add_u32_e32 v156, 3, v108
	v_add_u32_e32 v157, 7, v108
	v_mfma_f32_16x16x16_bf16 v[38:41], v[130:131], v[78:79], v[38:41]
	v_fma_f32 v60, v14, v60, -v152
	v_fma_f32 v61, v15, v61, -v153
	v_cndmask_b32_e32 v108, v108, v140, vcc
	v_lshlrev_b64 v[140:141], 5, v[108:109]
	v_mfma_f32_16x16x16_bf16 v[74:77], v[136:137], v[78:79], v[74:77]
	v_cndmask_b32_e32 v108, v142, v143, vcc
	v_lshl_add_u64 v[142:143], v[138:139], 0, v[140:141]
	v_lshlrev_b64 v[140:141], 5, v[108:109]
	v_mfma_f32_16x16x16_bf16 v[58:61], v[134:135], v[78:79], v[58:61]
	v_cndmask_b32_e32 v108, v144, v145, vcc
	v_pk_mul_f32 v[184:185], v[118:119], v[64:65]
	v_lshlrev_b32_e32 v164, 16, v78
	v_mfma_f32_16x16x16_bf16 v[54:57], v[126:127], v[78:79], v[54:57]
	v_and_b32_e32 v165, 0xffff0000, v78
	v_lshlrev_b32_e32 v206, 16, v79
	v_and_b32_e32 v207, 0xffff0000, v79
	v_lshl_add_u64 v[78:79], v[138:139], 0, v[140:141]
	v_lshlrev_b64 v[140:141], 5, v[108:109]
	v_cndmask_b32_e32 v108, v156, v157, vcc
	v_cvt_pk_bf16_f32 v157, v68, v69
	v_pk_mul_f32 v[186:187], v[88:89], v[62:63]
	v_pk_mul_f32 v[188:189], v[2:3], v[64:65]
	v_pk_mul_f32 v[190:191], v[86:87], v[62:63]
	v_pk_mul_f32 v[192:193], v[120:121], v[68:69]
	v_pk_mul_f32 v[196:197], v[6:7], v[68:69]
	v_pk_fma_f32 v[68:69], v[2:3], v[48:49], v[184:185] neg_lo:[0,0,1] neg_hi:[0,0,1]
	v_pk_mul_f32 v[184:185], v[96:97], v[70:71]
	v_cvt_pk_bf16_f32 v150, v46, v47
	v_cvt_pk_bf16_f32 v151, v48, v49
	v_cvt_pk_bf16_f32 v156, v66, v67
	v_cvt_pk_bf16_f32 v160, v70, v71
	v_pk_mul_f32 v[194:195], v[92:93], v[66:67]
	v_pk_mul_f32 v[198:199], v[90:91], v[66:67]
	v_pk_mul_f32 v[200:201], v[122:123], v[72:73]
	v_pk_fma_f32 v[66:67], v[86:87], v[46:47], v[186:187] neg_lo:[0,0,1] neg_hi:[0,0,1]
	v_pk_fma_f32 v[48:49], v[118:119], v[48:49], v[188:189]
	v_pk_fma_f32 v[46:47], v[88:89], v[46:47], v[190:191]
	v_pk_mul_f32 v[186:187], v[10:11], v[72:73]
	v_pk_mul_f32 v[188:189], v[94:95], v[70:71]
	v_pk_mul_f32 v[190:191], v[124:125], v[76:77]
	v_pk_fma_f32 v[70:71], v[94:95], v[38:39], v[184:185] neg_lo:[0,0,1] neg_hi:[0,0,1]
	v_pk_mul_f32 v[184:185], v[100:101], v[74:75]
	v_cvt_pk_bf16_f32 v152, v62, v63
	v_cvt_pk_bf16_f32 v153, v64, v65
	v_cvt_pk_bf16_f32 v159, v40, v41
	v_cvt_pk_bf16_f32 v161, v72, v73
	v_pk_fma_f32 v[72:73], v[10:11], v[40:41], v[200:201] neg_lo:[0,0,1] neg_hi:[0,0,1]
	v_pk_fma_f32 v[40:41], v[122:123], v[40:41], v[186:187]
	v_pk_fma_f32 v[186:187], v[14:15], v[60:61], v[190:191] neg_lo:[0,0,1] neg_hi:[0,0,1]
	v_pk_fma_f32 v[184:185], v[98:99], v[58:59], v[184:185] neg_lo:[0,0,1] neg_hi:[0,0,1]
	v_cvt_pk_bf16_f32 v154, v54, v55
	v_cvt_pk_bf16_f32 v155, v56, v57
	v_cvt_pk_bf16_f32 v158, v38, v39
	v_mfma_f32_16x16x32_bf16 v[62:65], v[30:33], v[150:153], 0
	v_fma_f32 v152, v6, v56, -v192
	v_fma_f32 v153, v7, v57, -v193
	v_pk_fma_f32 v[150:151], v[90:91], v[54:55], v[194:195] neg_lo:[0,0,1] neg_hi:[0,0,1]
	v_pk_fma_f32 v[56:57], v[120:121], v[56:57], v[196:197]
	v_pk_fma_f32 v[54:55], v[92:93], v[54:55], v[198:199]
	v_pk_fma_f32 v[38:39], v[96:97], v[38:39], v[188:189]
; #define MFMA16(A, B, Cc) __builtin_amdgcn_mfma_f32_16x16x32_bf16((A), (B), (Cc), 0, 0, 0)
; #define MFMA16K16(A, B, Cc) __builtin_amdgcn_mfma_f32_16x16x16bf16_1k(__builtin_bit_cast(bf16x4, (A)), __builtin_bit_cast(bf16x4, (B)), (Cc), 0, 0, 0)
; __device__ __forceinline__ unsigned pk2(float lo, float hi) { return pg8::cvt_pk_bf16(lo, hi); }
; __device__ __forceinline__ float bf_lo(unsigned w) { return __uint_as_float(w << 16); }
; __device__ __forceinline__ unsigned pk4f8(float a, float b, float c, float d) { int p = __builtin_amdgcn_cvt_pk_fp8_f32(sat8(a), sat8(b), 0, false); p = __builtin_amdgcn_cvt_pk_fp8_f32(sat8(c), sat8(d), p, true); return (unsigned)p; }
; __device__ __forceinline__ float bf_hi(unsigned w) { return __uint_as_float(w & 0xffff0000u); }
; __device__ __forceinline__ bf16x8 pack8(f32x4 lo, f32x4 hi) { v4u w; w.x = pk2(lo[0], lo[1]); w.y = pk2(lo[2], lo[3]); w.z = pk2(hi[0], hi[1]); w.w = pk2(hi[2], hi[3]); return __builtin_bit_cast(bf16x8, w); }
; __device__ __forceinline__ unsigned s5_output(const S5C& K, const f32x4 (&hre)[4], const f32x4 (&him)[4], v2u xq, v2u zq) {
;     f32x4 y = (f32x4){0.f, 0.f, 0.f, 0.f};
; #pragma unroll
;     for (int j = 0; j < 4; ++j) y = MFMA16(K.Cf[j], pack8(hre[j], him[j]), y);
;     const f32x4 xf = (f32x4){bf_lo(xq.x), bf_hi(xq.x), bf_lo(xq.y), bf_hi(xq.y)};
;     y = y + K.dsk * xf;
;     const v2u yb = (v2u){pk2(y[0], y[1]), pk2(y[2], y[3])};
;     const f32x4 gv = MFMA16K16(K.Wv, yb, K.bv), gg = MFMA16K16(K.Wg, yb, K.bg);
;     const f32x4 zf = (f32x4){bf_lo(zq.x), bf_hi(zq.x), bf_lo(zq.y), bf_hi(zq.y)};
;     f32x4 o;
; #pragma unroll
;     for (int r = 0; r < 4; ++r) o[r] = gv[r] * __builtin_amdgcn_rcpf(1.0f + __expf(-gg[r])) * zf[r];
;     return pk4f8(o[0], o[1], o[2], o[3]);
	v_pk_mul_f32 v[192:193], v[14:15], v[76:77]
	v_mfma_f32_16x16x16_bf16 v[186:189], v[134:135], v[80:81], v[184:187]
	v_fma_f32 v192, v124, v60, v192
	v_fma_f32 v193, v125, v61, v193
	ds_read2_b64 v[82:85], v163 offset0:8 offset1:12
	v_cvt_pk_bf16_f32 v182, v58, v59
	v_pk_mul_f32 v[184:185], v[98:99], v[74:75]
	v_mfma_f32_16x16x16_bf16 v[66:69], v[114:115], v[80:81], v[66:69]
	v_fma_f32 v190, v100, v58, v184
	v_fma_f32 v191, v101, v59, v185
	v_cvt_pk_bf16_f32 v183, v60, v61
	v_cvt_pk_bf16_f32 v185, v76, v77
	v_mfma_f32_16x16x16_bf16 v[46:49], v[116:117], v[80:81], v[46:49]
	v_lshlrev_b32_e32 v208, 16, v80
	v_and_b32_e32 v209, 0xffff0000, v80
	v_cvt_pk_bf16_f32 v184, v74, v75
	v_mfma_f32_16x16x16_bf16 v[54:57], v[128:129], v[80:81], v[54:57]
	v_lshlrev_b32_e32 v210, 16, v81
	s_nop 2
	v_pk_mul_f32 v[194:195], v[2:3], v[48:49]
	v_pk_mul_f32 v[196:197], v[86:87], v[46:47]
	v_mfma_f32_16x16x16_bf16 v[150:153], v[126:127], v[80:81], v[150:153]
	v_and_b32_e32 v211, 0xffff0000, v81
	v_pk_mul_f32 v[198:199], v[120:121], v[56:57]
	v_cvt_pk_bf16_f32 v77, v56, v57
	v_mfma_f32_16x16x16_bf16 v[38:41], v[132:133], v[80:81], v[38:41]
	v_mul_f32_e64 v200, v92, v54
	v_mul_f32_e64 v201, v93, v55
	v_pk_mul_f32 v[202:203], v[6:7], v[56:57]
	s_nop 0
	v_cvt_pk_bf16_f32 v75, v152, v153
	v_mfma_f32_16x16x16_bf16 v[190:193], v[136:137], v[80:81], v[190:193]
	v_cvt_pk_bf16_f32 v76, v54, v55
	v_pk_mul_f32 v[204:205], v[90:91], v[54:55]
	v_pk_mul_f32 v[216:217], v[122:123], v[40:41]
	v_mfma_f32_16x16x16_bf16 v[70:73], v[130:131], v[80:81], v[70:73]
	v_cvt_pk_bf16_f32 v74, v150, v151
	s_waitcnt lgkmcnt(0)
	v_lshlrev_b32_e32 v212, 16, v82
	v_and_b32_e32 v213, 0xffff0000, v82
	v_mfma_f32_16x16x32_bf16 v[58:61], v[50:53], v[154:157], v[62:65]
	v_mul_f32_e64 v154, v118, v48
	v_mul_f32_e64 v155, v119, v49
	v_pk_mul_f32 v[156:157], v[88:89], v[46:47]
	v_pk_fma_f32 v[56:57], v[2:3], v[68:69], v[154:155] neg_lo:[0,0,1] neg_hi:[0,0,1]
	v_cvt_pk_bf16_f32 v62, v66, v67
	v_cvt_pk_bf16_f32 v63, v68, v69
	v_cvt_pk_bf16_f32 v64, v46, v47
	v_cvt_pk_bf16_f32 v65, v48, v49
	v_pk_mul_f32 v[154:155], v[96:97], v[38:39]
	v_cvt_pk_bf16_f32 v80, v70, v71
	v_mfma_f32_16x16x32_bf16 v[46:49], v[30:33], v[62:65], 0
	v_fma_f32 v64, v118, v68, v194
	v_fma_f32 v65, v119, v69, v195
	v_pk_fma_f32 v[62:63], v[88:89], v[66:67], v[196:197]
	v_pk_fma_f32 v[68:69], v[6:7], v[152:153], v[198:199] neg_lo:[0,0,1] neg_hi:[0,0,1]
	v_pk_mul_f32 v[196:197], v[94:95], v[38:39]
	v_pk_mul_f32 v[198:199], v[124:125], v[192:193]
	v_pk_fma_f32 v[54:55], v[86:87], v[66:67], v[156:157] neg_lo:[0,0,1] neg_hi:[0,0,1]
	v_pk_mul_f32 v[194:195], v[10:11], v[40:41]
	v_pk_fma_f32 v[66:67], v[90:91], v[150:151], v[200:201] neg_lo:[0,0,1] neg_hi:[0,0,1]
	v_pk_fma_f32 v[152:153], v[120:121], v[152:153], v[202:203]
	v_pk_fma_f32 v[154:155], v[94:95], v[70:71], v[154:155] neg_lo:[0,0,1] neg_hi:[0,0,1]
	v_pk_mul_f32 v[200:201], v[100:101], v[190:191]
	v_pk_fma_f32 v[70:71], v[96:97], v[70:71], v[196:197]
	v_pk_mul_f32 v[202:203], v[14:15], v[192:193]
	v_pk_fma_f32 v[196:197], v[14:15], v[188:189], v[198:199] neg_lo:[0,0,1] neg_hi:[0,0,1]
	v_pk_mul_f32 v[198:199], v[98:99], v[190:191]
	v_cvt_pk_bf16_f32 v81, v72, v73
	v_mfma_f32_16x16x16_bf16 v[62:65], v[116:117], v[82:83], v[62:65]
	v_fma_f32 v150, v92, v150, v204
	v_fma_f32 v151, v93, v151, v205
	v_pk_fma_f32 v[156:157], v[10:11], v[72:73], v[216:217] neg_lo:[0,0,1] neg_hi:[0,0,1]
	v_pk_fma_f32 v[72:73], v[122:123], v[72:73], v[194:195]
	v_pk_fma_f32 v[194:195], v[98:99], v[186:187], v[200:201] neg_lo:[0,0,1] neg_hi:[0,0,1]
	v_pk_fma_f32 v[200:201], v[124:125], v[188:189], v[202:203]
	v_pk_fma_f32 v[198:199], v[100:101], v[186:187], v[198:199]
	v_lshlrev_b32_e32 v214, 16, v83
	v_and_b32_e32 v215, 0xffff0000, v83
	v_mfma_f32_16x16x16_bf16 v[54:57], v[114:115], v[82:83], v[54:57]
	v_cvt_pk_bf16_f32 v186, v186, v187
	v_cvt_pk_bf16_f32 v187, v188, v189
	v_cvt_pk_bf16_f32 v189, v192, v193
	v_mfma_f32_16x16x16_bf16 v[66:69], v[126:127], v[82:83], v[66:69]
	v_cvt_pk_bf16_f32 v188, v190, v191
	v_lshlrev_b32_e32 v144, 16, v84
	v_and_b32_e32 v145, 0xffff0000, v84
	v_mfma_f32_16x16x16_bf16 v[150:153], v[128:129], v[82:83], v[150:153]
	v_lshlrev_b32_e32 v146, 16, v85
	s_nop 2
	v_cvt_pk_bf16_f32 v190, v66, v67
	v_cvt_pk_bf16_f32 v191, v68, v69
	v_mfma_f32_16x16x16_bf16 v[154:157], v[130:131], v[82:83], v[154:157]
	v_and_b32_e32 v147, 0xffff0000, v85
	v_cvt_pk_bf16_f32 v192, v150, v151
	v_cvt_pk_bf16_f32 v193, v152, v153
	v_mfma_f32_16x16x16_bf16 v[70:73], v[132:133], v[82:83], v[70:73]
	v_mul_f32_e64 v216, v6, v152
	v_mul_f32_e64 v217, v7, v153
	v_pk_mul_f32 v[218:219], v[90:91], v[150:151]
	s_nop 0
	v_cvt_pk_bf16_f32 v202, v154, v155
	v_mfma_f32_16x16x16_bf16 v[194:197], v[134:135], v[82:83], v[194:197]
	v_cvt_pk_bf16_f32 v203, v156, v157
	s_nop 0
	v_cvt_pk_bf16_f32 v204, v70, v71
	v_cvt_pk_bf16_f32 v205, v72, v73
	v_mfma_f32_16x16x16_bf16 v[198:201], v[136:137], v[82:83], v[198:201]
	v_cvt_pk_bf16_f32 v82, v38, v39
	v_cvt_pk_bf16_f32 v83, v40, v41
	v_pk_mul_f32 v[220:221], v[122:123], v[72:73]
	v_mfma_f32_16x16x32_bf16 v[38:41], v[42:45], v[158:161], v[58:61]
	v_lshlrev_b64 v[148:149], 5, v[108:109]
	v_mov_b32_e32 v166, 0
	v_mov_b32_e32 v171, v109
	v_pk_mul_f32 v[58:59], v[118:119], v[64:65]
	v_pk_mul_f32 v[60:61], v[88:89], v[62:63]
	v_mfma_f32_16x16x32_bf16 v[158:161], v[50:53], v[74:77], v[46:49]
	v_mul_f32_e64 v74, v120, v152
	v_mul_f32_e64 v75, v121, v153
	v_pk_mul_f32 v[76:77], v[92:93], v[150:151]
	v_mov_b32_e32 v176, v109
	v_cvt_pk_bf16_f32 v46, v54, v55
	v_cvt_pk_bf16_f32 v47, v56, v57
	v_cvt_pk_bf16_f32 v48, v62, v63
	v_cvt_pk_bf16_f32 v49, v64, v65
	v_pk_mul_f32 v[64:65], v[2:3], v[64:65]
; #define MFMA16(A, B, Cc) __builtin_amdgcn_mfma_f32_16x16x32_bf16((A), (B), (Cc), 0, 0, 0)
; #define MFMA16K16(A, B, Cc) __builtin_amdgcn_mfma_f32_16x16x16bf16_1k(__builtin_bit_cast(bf16x4, (A)), __builtin_bit_cast(bf16x4, (B)), (Cc), 0, 0, 0)
; __device__ __forceinline__ unsigned pk2(float lo, float hi) { return pg8::cvt_pk_bf16(lo, hi); }
; __device__ __forceinline__ float bf_lo(unsigned w) { return __uint_as_float(w << 16); }
; __device__ __forceinline__ unsigned pk4f8(float a, float b, float c, float d) { int p = __builtin_amdgcn_cvt_pk_fp8_f32(sat8(a), sat8(b), 0, false); p = __builtin_amdgcn_cvt_pk_fp8_f32(sat8(c), sat8(d), p, true); return (unsigned)p; }
; __device__ __forceinline__ float bf_hi(unsigned w) { return __uint_as_float(w & 0xffff0000u); }
; __device__ __forceinline__ bf16x8 pack8(f32x4 lo, f32x4 hi) { v4u w; w.x = pk2(lo[0], lo[1]); w.y = pk2(lo[2], lo[3]); w.z = pk2(hi[0], hi[1]); w.w = pk2(hi[2], hi[3]); return __builtin_bit_cast(bf16x8, w); }
; __device__ __forceinline__ unsigned s5_output(const S5C& K, const f32x4 (&hre)[4], const f32x4 (&him)[4], v2u xq, v2u zq) {
;     f32x4 y = (f32x4){0.f, 0.f, 0.f, 0.f};
; #pragma unroll
;     for (int j = 0; j < 4; ++j) y = MFMA16(K.Cf[j], pack8(hre[j], him[j]), y);
;     const f32x4 xf = (f32x4){bf_lo(xq.x), bf_hi(xq.x), bf_lo(xq.y), bf_hi(xq.y)};
;     y = y + K.dsk * xf;
;     const v2u yb = (v2u){pk2(y[0], y[1]), pk2(y[2], y[3])};
;     const f32x4 gv = MFMA16K16(K.Wv, yb, K.bv), gg = MFMA16K16(K.Wg, yb, K.bg);
;     const f32x4 zf = (f32x4){bf_lo(zq.x), bf_hi(zq.x), bf_lo(zq.y), bf_hi(zq.y)};
;     f32x4 o;
; #pragma unroll
;     for (int r = 0; r < 4; ++r) o[r] = gv[r] * __builtin_amdgcn_rcpf(1.0f + __expf(-gg[r])) * zf[r];
;     return pk4f8(o[0], o[1], o[2], o[3]);
	v_pk_mul_f32 v[62:63], v[86:87], v[62:63]
	v_mfma_f32_16x16x32_bf16 v[182:185], v[34:37], v[182:185], v[38:41]
	v_mov_b32_e32 v225, v109
	v_lshl_add_u64 v[140:141], v[138:139], 0, v[140:141]
	v_lshl_add_u64 v[148:149], v[138:139], 0, v[148:149]
	v_pk_fma_f32 v[40:41], v[2:3], v[56:57], v[58:59] neg_lo:[0,0,1] neg_hi:[0,0,1]
	v_pk_fma_f32 v[38:39], v[86:87], v[54:55], v[60:61] neg_lo:[0,0,1] neg_hi:[0,0,1]
	v_mfma_f32_16x16x32_bf16 v[150:153], v[30:33], v[46:49], 0
	v_mul_f32_e64 v58, v96, v70
	v_mul_f32_e64 v59, v97, v71
	v_pk_mul_f32 v[60:61], v[10:11], v[72:73]
	v_pk_mul_f32 v[70:71], v[94:95], v[70:71]
	v_mfma_f32_16x16x16_bf16 v[46:49], v[114:115], v[84:85], v[38:41]
	v_fma_f32 v60, v122, v156, v60
	v_fma_f32 v61, v123, v157, v61
	v_add_u32_e32 v163, 0x80, v163
	s_add_i32 s0, s0, 4
	v_pk_fma_f32 v[40:41], v[118:119], v[56:57], v[64:65]
	v_pk_fma_f32 v[38:39], v[88:89], v[54:55], v[62:63]
	v_mfma_f32_16x16x32_bf16 v[80:83], v[42:45], v[80:83], v[158:161]
	s_and_b64 vcc, exec, vcc
	v_mfma_f32_16x16x16_bf16 v[62:65], v[116:117], v[84:85], v[38:41]
	s_nop 0
	v_fma_f32 v158, v18, v164, v182
	v_fma_f32 v159, v19, v165, v183
	v_cvt_pk_bf16_f32 v164, v158, v159
	v_pk_fma_f32 v[40:41], v[6:7], v[68:69], v[74:75] neg_lo:[0,0,1] neg_hi:[0,0,1]
	v_pk_fma_f32 v[38:39], v[90:91], v[66:67], v[76:77] neg_lo:[0,0,1] neg_hi:[0,0,1]
	v_pk_mul_f32 v[74:75], v[124:125], v[200:201]
	v_pk_mul_f32 v[76:77], v[100:101], v[198:199]
	v_mfma_f32_16x16x16_bf16 v[54:57], v[126:127], v[84:85], v[38:41]
	v_cvt_pk_bf16_f32 v158, v46, v47
	v_cvt_pk_bf16_f32 v159, v48, v49
	v_cvt_pk_bf16_f32 v160, v62, v63
	v_pk_fma_f32 v[40:41], v[120:121], v[68:69], v[216:217]
	v_pk_fma_f32 v[38:39], v[92:93], v[66:67], v[218:219]
	v_mfma_f32_16x16x32_bf16 v[150:153], v[50:53], v[190:193], v[150:153]
	v_cvt_pk_bf16_f32 v161, v64, v65
	v_mfma_f32_16x16x16_bf16 v[66:69], v[128:129], v[84:85], v[38:41]
	s_nop 2
	v_fma_f32 v38, v94, v154, -v58
	v_fma_f32 v39, v95, v155, -v59
	v_pk_fma_f32 v[58:59], v[96:97], v[154:155], v[70:71]
	v_pk_mul_f32 v[154:155], v[14:15], v[200:201]
	v_pk_fma_f32 v[40:41], v[10:11], v[156:157], v[220:221] neg_lo:[0,0,1] neg_hi:[0,0,1]
	v_mfma_f32_16x16x16_bf16 v[70:73], v[132:133], v[84:85], v[58:61]
	v_cvt_pk_bf16_f32 v156, v198, v199
	v_cvt_pk_bf16_f32 v157, v200, v201
	s_nop 0
	v_pk_fma_f32 v[60:61], v[14:15], v[196:197], v[74:75] neg_lo:[0,0,1] neg_hi:[0,0,1]
	v_pk_mul_f32 v[74:75], v[98:99], v[198:199]
	v_pk_fma_f32 v[58:59], v[98:99], v[194:195], v[76:77] neg_lo:[0,0,1] neg_hi:[0,0,1]
	v_pk_fma_f32 v[76:77], v[124:125], v[196:197], v[154:155]
	v_pk_fma_f32 v[74:75], v[100:101], v[194:195], v[74:75]
	v_mfma_f32_16x16x16_bf16 v[38:41], v[130:131], v[84:85], v[38:41]
	v_cvt_pk_bf16_f32 v154, v194, v195
	v_cvt_pk_bf16_f32 v155, v196, v197
	v_cvt_pk_bf16_f32 v194, v54, v55
	v_mfma_f32_16x16x16_bf16 v[58:61], v[134:135], v[84:85], v[58:61]
	v_cvt_pk_bf16_f32 v195, v56, v57
	v_cvt_pk_bf16_f32 v196, v66, v67
	v_cvt_pk_bf16_f32 v197, v68, v69
	v_mfma_f32_16x16x16_bf16 v[74:77], v[136:137], v[84:85], v[74:77]
	v_fma_f32 v84, v20, v206, v184
	v_fma_f32 v85, v21, v207, v185
	s_nop 1
	v_cvt_pk_bf16_f32 v198, v58, v59
	v_cvt_pk_bf16_f32 v165, v84, v85
	v_mfma_f32_16x16x32_bf16 v[80:83], v[34:37], v[186:189], v[80:83]
	v_cvt_pk_bf16_f32 v186, v38, v39
	v_cvt_pk_bf16_f32 v187, v40, v41
	v_cvt_pk_bf16_f32 v188, v70, v71
	v_mfma_f32_16x16x16_bf16 v[190:193], v[104:105], v[164:165], v[26:29]
	v_cvt_pk_bf16_f32 v189, v72, v73
	s_nop 2
	v_pk_fma_f32 v[80:81], v[18:19], v[208:209], v[80:81]
	v_cvt_pk_bf16_f32 v199, v60, v61
	v_mfma_f32_16x16x32_bf16 v[158:161], v[30:33], v[158:161], 0
	v_cvt_pk_bf16_f32 v80, v80, v81
	v_mul_f32_e32 v3, 0xbfb8aa3b, v190
	v_mul_f32_e32 v7, 0xbfb8aa3b, v191
	v_mfma_f32_16x16x32_bf16 v[150:153], v[42:45], v[202:205], v[150:153]
	v_exp_f32_e32 v3, v3
	v_exp_f32_e32 v7, v7
	v_mul_f32_e32 v11, 0xbfb8aa3b, v192
	v_mfma_f32_16x16x16_bf16 v[182:185], v[102:103], v[164:165], v[22:25]
	v_fma_f32 v164, v20, v210, v82
	v_fma_f32 v165, v21, v211, v83
	v_mul_f32_e32 v15, 0xbfb8aa3b, v193
	v_cvt_pk_bf16_f32 v81, v164, v165
	v_mfma_f32_16x16x32_bf16 v[82:85], v[50:53], v[194:197], v[158:161]
	v_exp_f32_e32 v11, v11
	v_exp_f32_e32 v15, v15
	v_add_f32_e32 v3, 1.0, v3
	v_mfma_f32_16x16x32_bf16 v[150:153], v[34:37], v[154:157], v[150:153]
	v_add_f32_e32 v7, 1.0, v7
	v_rcp_f32_e32 v3, v3
	v_rcp_f32_e32 v7, v7
	v_mfma_f32_16x16x16_bf16 v[194:197], v[104:105], v[80:81], v[26:29]
	v_cvt_pk_bf16_f32 v200, v74, v75
	s_nop 2
	v_pk_fma_f32 v[150:151], v[18:19], v[212:213], v[150:151]
	v_cvt_pk_bf16_f32 v201, v76, v77
	v_mfma_f32_16x16x16_bf16 v[158:161], v[102:103], v[80:81], v[22:25]
	v_cvt_pk_bf16_f32 v154, v150, v151
	v_mul_f32_e32 v108, 0xbfb8aa3b, v194
	v_mul_f32_e32 v119, 0xbfb8aa3b, v195
	v_mfma_f32_16x16x32_bf16 v[80:83], v[42:45], v[186:189], v[82:85]
	v_exp_f32_e32 v108, v108
	v_exp_f32_e32 v119, v119
	v_add_f32_e32 v11, 1.0, v11
	v_pk_fma_f32 v[84:85], v[20:21], v[214:215], v[152:153]
	v_mfma_f32_16x16x32_bf16 v[80:83], v[34:37], v[198:201], v[80:83]
	v_cvt_pk_bf16_f32 v155, v84, v85
	v_mul_f32_e32 v84, 0xbfb8aa3b, v196
	v_mul_f32_e32 v85, 0xbfb8aa3b, v197
	v_exp_f32_e32 v84, v84
	v_mfma_f32_16x16x16_bf16 v[150:153], v[102:103], v[154:155], v[22:25]
	v_exp_f32_e32 v85, v85
	v_add_f32_e32 v15, 1.0, v15
	v_rcp_f32_e32 v11, v11
	v_mfma_f32_16x16x16_bf16 v[154:157], v[104:105], v[154:155], v[26:29]
	v_rcp_f32_e32 v15, v15
	v_mul_f32_e32 v3, v182, v3
	v_mul_f32_e32 v7, v183, v7
	s_waitcnt vmcnt(0)
; #define LAS __attribute__((address_space(3)))
; #define MFMA16(A, B, Cc) __builtin_amdgcn_mfma_f32_16x16x32_bf16((A), (B), (Cc), 0, 0, 0)
; #define MFMA16K16(A, B, Cc) __builtin_amdgcn_mfma_f32_16x16x16bf16_1k(__builtin_bit_cast(bf16x4, (A)), __builtin_bit_cast(bf16x4, (B)), (Cc), 0, 0, 0)
; __device__ __forceinline__ unsigned pk2(float lo, float hi) { return pg8::cvt_pk_bf16(lo, hi); }
; __device__ __forceinline__ float bf_lo(unsigned w) { return __uint_as_float(w << 16); }
; __device__ __forceinline__ unsigned pk4f8(float a, float b, float c, float d) { int p = __builtin_amdgcn_cvt_pk_fp8_f32(sat8(a), sat8(b), 0, false); p = __builtin_amdgcn_cvt_pk_fp8_f32(sat8(c), sat8(d), p, true); return (unsigned)p; }
; __device__ __forceinline__ float bf_hi(unsigned w) { return __uint_as_float(w & 0xffff0000u); }
; __device__ __forceinline__ unsigned s5_output(const S5C& K, const f32x4 (&hre)[4], const f32x4 (&him)[4], v2u xq, v2u zq) {
;     f32x4 y = (f32x4){0.f, 0.f, 0.f, 0.f};
; #pragma unroll
;     for (int j = 0; j < 4; ++j) y = MFMA16(K.Cf[j], pack8(hre[j], him[j]), y);
;     const f32x4 xf = (f32x4){bf_lo(xq.x), bf_hi(xq.x), bf_lo(xq.y), bf_hi(xq.y)};
;     y = y + K.dsk * xf;
;     const v2u yb = (v2u){pk2(y[0], y[1]), pk2(y[2], y[3])};
;     const f32x4 gv = MFMA16K16(K.Wv, yb, K.bv), gg = MFMA16K16(K.Wg, yb, K.bg);
;     const f32x4 zf = (f32x4){bf_lo(zq.x), bf_hi(zq.x), bf_lo(zq.y), bf_hi(zq.y)};
;     f32x4 o;
; #pragma unroll
;     for (int r = 0; r < 4; ++r) o[r] = gv[r] * __builtin_amdgcn_rcpf(1.0f + __expf(-gg[r])) * zf[r];
;     return pk4f8(o[0], o[1], o[2], o[3]);
; __device__ __forceinline__ void s5_prompt_task(const Args& a, const Ctx& C, int b, int g, v4u (&xv)[8]) {
;     ...
; #pragma unroll 1
;     for (int t0 = 0; t0 < 16; t0 += 4) {
; #pragma unroll
;         for (int u = 0; u < 4; ++u) { const int t = t0 + u, tok = 16 * chunk + t;
;             const v2u xq = *(const LAS v2u*)(xsl + t * 32);
;             S5_UPDATE(K, hre, him, xq);
;             *(unsigned*)((unsigned char*)Y + (row0 + tok) * DM + DA + g * 16 + 4 * q) = s5_output(K, hre, him, xq, zq[u]);
;             const size_t tn = row0 + ((t + 4 < 16) ? tok + 4 : tok);
;             zq[u] = __builtin_nontemporal_load((const v2u*)(ZBg + (size_t)(tn - row0) * 16 + 4 * q)); } }
	v_lshlrev_b32_e32 v177, 16, v230
	v_and_b32_e32 v178, 0xffff0000, v230
	v_lshlrev_b32_e32 v179, 16, v231
	v_and_b32_e32 v180, 0xffff0000, v231
	v_lshlrev_b32_e32 v167, 16, v226
	v_and_b32_e32 v168, 0xffff0000, v226
	v_lshlrev_b32_e32 v169, 16, v227
	v_and_b32_e32 v170, 0xffff0000, v227
	v_lshlrev_b32_e32 v181, 16, v232
	v_and_b32_e32 v222, 0xffff0000, v232
	v_lshlrev_b32_e32 v223, 16, v233
	v_and_b32_e32 v224, 0xffff0000, v233
	v_lshlrev_b32_e32 v172, 16, v228
	v_and_b32_e32 v173, 0xffff0000, v228
	v_lshlrev_b32_e32 v174, 16, v229
	v_and_b32_e32 v175, 0xffff0000, v229
	v_mul_f32_e32 v3, v3, v167
	v_mul_f32_e32 v7, v7, v168
	v_add_f32_e32 v108, 1.0, v108
	v_add_f32_e32 v119, 1.0, v119
	v_add_f32_e32 v84, 1.0, v84
	v_add_f32_e32 v85, 1.0, v85
	v_med3_f32 v3, v3, s1, v111
	v_med3_f32 v7, v7, s1, v111
	v_rcp_f32_e32 v108, v108
	v_rcp_f32_e32 v119, v119
	v_rcp_f32_e32 v121, v84
	v_mul_f32_e32 v84, 0xbfb8aa3b, v154
	v_pk_fma_f32 v[82:83], v[20:21], v[146:147], v[82:83]
	v_pk_fma_f32 v[80:81], v[18:19], v[144:145], v[80:81]
	v_rcp_f32_e32 v123, v85
	v_cvt_pk_fp8_f32 v166, v3, v7
	v_exp_f32_e32 v3, v84
	v_cvt_pk_bf16_f32 v84, v80, v81
	v_cvt_pk_bf16_f32 v85, v82, v83
	v_mul_f32_e32 v11, v184, v11
	v_mul_f32_e32 v15, v185, v15
	v_mfma_f32_16x16x16_bf16 v[144:147], v[104:105], v[84:85], v[26:29]
	v_mul_f32_e32 v11, v11, v169
	v_mul_f32_e32 v15, v15, v170
	v_mul_f32_e32 v125, 0xbfb8aa3b, v155
	v_med3_f32 v11, v11, s1, v111
	v_med3_f32 v15, v15, s1, v111
	v_mul_f32_e32 v154, 0xbfb8aa3b, v156
	v_mul_f32_e32 v155, 0xbfb8aa3b, v157
	v_mfma_f32_16x16x16_bf16 v[80:83], v[102:103], v[84:85], v[22:25]
	v_exp_f32_e32 v7, v125
	v_mul_f32_e32 v84, v158, v108
	v_mul_f32_e32 v85, v159, v119
	v_exp_f32_e32 v125, v154
	v_exp_f32_e32 v154, v155
	v_cvt_pk_fp8_f32 v166, v11, v15 op_sel:[0,0,1]
	v_mul_f32_e32 v11, v84, v172
	v_mul_f32_e32 v15, v85, v173
	v_mul_f32_e32 v108, v160, v121
	v_mul_f32_e32 v119, v161, v123
	v_med3_f32 v11, v11, s1, v111
	v_med3_f32 v15, v15, s1, v111
	v_mul_f32_e32 v121, 0xbfb8aa3b, v144
	v_mul_f32_e32 v123, 0xbfb8aa3b, v145
	v_cvt_pk_fp8_f32 v171, v11, v15
	v_exp_f32_e32 v11, v121
	v_exp_f32_e32 v15, v123
	v_add_f32_e32 v3, 1.0, v3
	v_add_f32_e32 v7, 1.0, v7
	v_mul_f32_e32 v84, v108, v174
	v_mul_f32_e32 v85, v119, v175
	v_add_f32_e32 v108, 1.0, v125
	v_add_f32_e32 v119, 1.0, v154
	v_rcp_f32_e32 v3, v3
	v_rcp_f32_e32 v7, v7
	v_rcp_f32_e32 v108, v108
	v_rcp_f32_e32 v119, v119
	v_mul_f32_e32 v125, 0xbfb8aa3b, v146
	v_mul_f32_e32 v144, 0xbfb8aa3b, v147
	v_exp_f32_e32 v121, v125
	v_exp_f32_e32 v123, v144
	v_add_f32_e32 v11, 1.0, v11
	v_add_f32_e32 v15, 1.0, v15
	v_rcp_f32_e32 v11, v11
	v_rcp_f32_e32 v15, v15
	v_mul_f32_e32 v3, v150, v3
	v_mul_f32_e32 v7, v151, v7
	v_med3_f32 v84, v84, s1, v111
	v_med3_f32 v85, v85, s1, v111
	global_store_dword v[112:113], v166, off offset:-2048
	v_mul_f32_e32 v108, v152, v108
	v_mul_f32_e32 v112, v153, v119
	v_mul_f32_e32 v3, v3, v177
	v_mul_f32_e32 v7, v7, v178
	v_cvt_pk_fp8_f32 v171, v84, v85 op_sel:[0,0,1]
	v_mul_f32_e32 v84, v108, v179
	v_mul_f32_e32 v85, v112, v180
	v_add_f32_e32 v108, 1.0, v121
	v_add_f32_e32 v112, 1.0, v123
	v_med3_f32 v3, v3, s1, v111
	v_med3_f32 v7, v7, s1, v111
	v_rcp_f32_e32 v108, v108
	v_rcp_f32_e32 v112, v112
	v_cvt_pk_fp8_f32 v176, v3, v7
	v_mul_f32_e32 v3, v80, v11
	v_mul_f32_e32 v7, v81, v15
	v_mul_f32_e32 v3, v3, v181
	v_mul_f32_e32 v7, v7, v222
	v_med3_f32 v3, v3, s1, v111
	v_med3_f32 v7, v7, s1, v111
	v_cvt_pk_fp8_f32 v225, v3, v7
	v_mul_f32_e32 v11, v82, v108
	v_mul_f32_e32 v15, v83, v112
	v_med3_f32 v84, v84, s1, v111
	v_med3_f32 v85, v85, s1, v111
	v_mul_f32_e32 v11, v11, v223
	v_mul_f32_e32 v3, v15, v224
	v_cvt_pk_fp8_f32 v176, v84, v85 op_sel:[0,0,1]
	v_med3_f32 v7, v11, s1, v111
	v_med3_f32 v3, v3, s1, v111
	v_cvt_pk_fp8_f32 v225, v7, v3 op_sel:[0,0,1]
	global_load_dwordx2 v[226:227], v[142:143], off nt
	s_nop 0
	global_store_dword v[106:107], v171, off offset:-4096
	global_load_dwordx2 v[228:229], v[78:79], off nt
	s_nop 0
	global_store_dword v[106:107], v176, off offset:-2048
	global_load_dwordx2 v[230:231], v[140:141], off nt
	s_nop 0
	global_store_dword v[106:107], v225, off
	global_load_dwordx2 v[232:233], v[148:149], off nt
	v_lshl_add_u64 v[106:107], v[106:107], 0, s[4:5]
	s_cbranch_vccnz .LBB0_988
